# stack + fused LN epilogue row statistics: xor-16/32 lane exchanges via v_permlane16/32_swap instead of 32 serialized ds_bpermute round trips
# baseline (speedup 1.0000x reference)
.LBB0_333:
	v_readlane_b32 s6, v253, 9
	v_readlane_b32 s7, v253, 10
	s_lshl_b64 s[6:7], s[6:7], 2
	s_add_u32 s2, s18, s6
	s_addc_u32 s6, s19, s7
	s_add_u32 s62, s2, 0x100000
	s_addc_u32 s63, s6, 0
	s_lshl_b32 s2, s50, 2
	s_add_u32 s2, s62, s2
	s_addc_u32 s12, s63, 0
	s_lshl_b64 s[6:7], s[66:67], 2
	s_add_u32 s8, s8, s6
	s_addc_u32 s9, s9, s7
	s_add_u32 s6, s10, s6
	s_addc_u32 s7, s11, s7
	s_lshl_b32 s24, s82, 8
	s_waitcnt vmcnt(0)
	s_barrier
	v_mbcnt_lo_u32_b32 v0, -1, 0
	v_mbcnt_hi_u32_b32 v0, -1, v0
	s_lshl_b32 s11, s22, 8
	v_ashrrev_i32_e32 v130, 2, v0
	s_ashr_i32 s25, s24, 31
	s_ashr_i32 s10, s82, 3
	s_or_b32 s11, s11, s43
	v_and_b32_e32 v130, -4, v130
	s_lshl_b64 s[26:27], s[24:25], 11
	v_add_u32_e32 v180, s11, v130
	s_add_u32 s14, s28, s26
	v_and_or_b32 v196, v0, 15, s17
	s_addc_u32 s15, s29, s27
	v_ashrrev_i32_e32 v181, 31, v180
	v_ashrrev_i32_e32 v197, 31, v196
	v_or_b32_e32 v194, 16, v196
	v_lshl_add_u64 v[138:139], v[180:181], 1, s[14:15]
	v_lshlrev_b64 v[130:131], 11, v[196:197]
	v_ashrrev_i32_e32 v195, 31, v194
	v_or_b32_e32 v192, 32, v196
	v_add_u32_e32 v184, 0xa0, v196
	v_add_u32_e32 v188, 0x80, v196
	v_lshl_add_u64 v[142:143], v[138:139], 0, v[130:131]
	v_lshlrev_b64 v[130:131], 11, v[194:195]
	v_ashrrev_i32_e32 v193, 31, v192
	v_or_b32_e32 v190, 48, v196
	v_add_u32_e32 v186, 0x90, v196
	v_ashrrev_i32_e32 v185, 31, v184
	v_add_u32_e32 v182, 0xb0, v196
	s_mul_hi_i32 s11, s10, 0x2400
	s_mulk_i32 s10, 0x2400
	v_ashrrev_i32_e32 v189, 31, v188
	v_lshl_add_u64 v[144:145], v[138:139], 0, v[130:131]
	v_lshlrev_b64 v[130:131], 11, v[192:193]
	v_ashrrev_i32_e32 v191, 31, v190
	v_ashrrev_i32_e32 v187, 31, v186
	v_lshlrev_b64 v[152:153], 11, v[184:185]
	v_ashrrev_i32_e32 v183, 31, v182
	v_lshlrev_b64 v[140:141], 11, v[188:189]
	v_lshl_add_u64 v[146:147], v[138:139], 0, v[130:131]
	v_lshlrev_b64 v[130:131], 11, v[190:191]
	v_lshlrev_b64 v[150:151], 11, v[186:187]
	v_lshl_add_u64 v[162:163], v[138:139], 0, v[152:153]
	v_lshlrev_b64 v[152:153], 11, v[182:183]
	s_lshl_b64 s[28:29], s[10:11], 2
	v_lshl_add_u64 v[148:149], v[138:139], 0, v[130:131]
	v_lshl_add_u64 v[140:141], v[138:139], 0, v[140:141]
	v_lshl_add_u64 v[150:151], v[138:139], 0, v[150:151]
	v_lshl_add_u64 v[138:139], v[138:139], 0, v[152:153]
	s_add_u32 s10, s2, s28
	global_load_dwordx2 v[136:137], v[142:143], off
	global_load_dwordx2 v[134:135], v[144:145], off
	global_load_dwordx2 v[132:133], v[146:147], off
	global_load_dwordx2 v[224:225], v[140:141], off
	global_load_dwordx2 v[130:131], v[148:149], off
	global_load_dwordx2 v[222:223], v[150:151], off
	global_load_dwordx2 v[220:221], v[162:163], off
	global_load_dwordx2 v[218:219], v[138:139], off
	global_load_dwordx2 v[216:217], v[142:143], off offset:32
	global_load_dwordx2 v[214:215], v[144:145], off offset:32
	global_load_dwordx2 v[212:213], v[146:147], off offset:32
	global_load_dwordx2 v[210:211], v[148:149], off offset:32
	global_load_dwordx2 v[208:209], v[140:141], off offset:32
	global_load_dwordx2 v[206:207], v[150:151], off offset:32
	global_load_dwordx2 v[204:205], v[162:163], off offset:32
	global_load_dwordx2 v[202:203], v[138:139], off offset:32
	global_load_dwordx2 v[200:201], v[142:143], off offset:256
	global_load_dwordx2 v[176:177], v[144:145], off offset:256
	global_load_dwordx2 v[174:175], v[146:147], off offset:256
	global_load_dwordx2 v[172:173], v[148:149], off offset:256
	global_load_dwordx2 v[170:171], v[140:141], off offset:256
	global_load_dwordx2 v[168:169], v[150:151], off offset:256
	global_load_dwordx2 v[166:167], v[162:163], off offset:256
	global_load_dwordx2 v[164:165], v[138:139], off offset:256
	global_load_dwordx2 v[160:161], v[142:143], off offset:288
	global_load_dwordx2 v[158:159], v[144:145], off offset:288
	global_load_dwordx2 v[156:157], v[146:147], off offset:288
	global_load_dwordx2 v[154:155], v[148:149], off offset:288
	global_load_dwordx2 v[152:153], v[140:141], off offset:288
	s_nop 0
	global_load_dwordx2 v[150:151], v[150:151], off offset:288
	s_nop 0
	global_load_dwordx2 v[148:149], v[162:163], off offset:288
	global_load_dwordx2 v[146:147], v[138:139], off offset:288
	s_addc_u32 s11, s12, s29
	v_lshlrev_b64 v[162:163], 2, v[180:181]
	v_lshl_add_u64 v[198:199], s[10:11], 0, v[162:163]
	global_load_dwordx4 v[138:141], v[198:199], off
	global_load_dwordx4 v[232:235], v[198:199], off offset:64
	global_load_dwordx4 v[236:239], v[198:199], off offset:512
	global_load_dwordx4 v[240:243], v[198:199], off offset:576
	s_waitcnt vmcnt(0)
	s_lshl_b32 s2, s53, 3
	s_mov_b32 s42, s50
	s_add_i32 s2, s2, 0
	v_pk_mul_f32 v[228:229], v[140:141], 0.5 op_sel_hi:[1, 0]
	v_pk_mul_f32 v[226:227], v[138:139], 0.5 op_sel_hi:[1, 0]
	v_cvt_f32_f16_e32 v138, v137
	v_cvt_f32_f16_sdwa v139, v137 dst_sel:DWORD dst_unused:UNUSED_PAD src0_sel:WORD_1
	v_cvt_f32_f16_e32 v140, v136
	v_cvt_f32_f16_sdwa v141, v136 dst_sel:DWORD dst_unused:UNUSED_PAD src0_sel:WORD_1
	v_pk_mul_f32 v[138:139], v[138:139], s[90:91] op_sel_hi:[1, 0]
	s_nop 0
	v_pk_fma_f32 v[144:145], v[128:129], v[228:229], v[138:139]
	v_pk_mul_f32 v[136:137], v[140:141], s[90:91] op_sel_hi:[1, 0]
	v_cvt_f32_f16_e32 v128, v134
	v_pk_fma_f32 v[142:143], v[126:127], v[226:227], v[136:137]
	v_cvt_f32_f16_e32 v126, v135
	v_cvt_f32_f16_sdwa v127, v135 dst_sel:DWORD dst_unused:UNUSED_PAD src0_sel:WORD_1
	v_cvt_f32_f16_sdwa v129, v134 dst_sel:DWORD dst_unused:UNUSED_PAD src0_sel:WORD_1
	v_pk_mul_f32 v[126:127], v[126:127], s[90:91] op_sel_hi:[1, 0]
	v_pk_mul_f32 v[128:129], v[128:129], s[90:91] op_sel_hi:[1, 0]
	v_pk_fma_f32 v[140:141], v[124:125], v[228:229], v[126:127]
	v_pk_fma_f32 v[138:139], v[122:123], v[226:227], v[128:129]
	v_cvt_f32_f16_e32 v122, v133
	v_cvt_f32_f16_sdwa v123, v133 dst_sel:DWORD dst_unused:UNUSED_PAD src0_sel:WORD_1
	v_cvt_f32_f16_e32 v124, v132
	v_cvt_f32_f16_sdwa v125, v132 dst_sel:DWORD dst_unused:UNUSED_PAD src0_sel:WORD_1
	v_pk_mul_f32 v[122:123], v[122:123], s[90:91] op_sel_hi:[1, 0]
	v_pk_mul_f32 v[124:125], v[124:125], s[90:91] op_sel_hi:[1, 0]
	v_pk_fma_f32 v[136:137], v[120:121], v[228:229], v[122:123]
	v_pk_fma_f32 v[134:135], v[118:119], v[226:227], v[124:125]
	v_cvt_f32_f16_e32 v118, v131
	v_cvt_f32_f16_sdwa v119, v131 dst_sel:DWORD dst_unused:UNUSED_PAD src0_sel:WORD_1
	v_cvt_f32_f16_e32 v120, v130
	v_cvt_f32_f16_sdwa v121, v130 dst_sel:DWORD dst_unused:UNUSED_PAD src0_sel:WORD_1
	v_pk_mul_f32 v[118:119], v[118:119], s[90:91] op_sel_hi:[1, 0]
	v_pk_mul_f32 v[120:121], v[120:121], s[90:91] op_sel_hi:[1, 0]
	v_pk_fma_f32 v[132:133], v[116:117], v[228:229], v[118:119]
	v_pk_fma_f32 v[130:131], v[114:115], v[226:227], v[120:121]
	v_cvt_f32_f16_e32 v114, v225
	v_cvt_f32_f16_sdwa v115, v225 dst_sel:DWORD dst_unused:UNUSED_PAD src0_sel:WORD_1
	v_cvt_f32_f16_e32 v116, v224
	v_cvt_f32_f16_sdwa v117, v224 dst_sel:DWORD dst_unused:UNUSED_PAD src0_sel:WORD_1
	v_pk_mul_f32 v[114:115], v[114:115], s[90:91] op_sel_hi:[1, 0]
	v_pk_mul_f32 v[116:117], v[116:117], s[90:91] op_sel_hi:[1, 0]
	v_pk_fma_f32 v[128:129], v[112:113], v[228:229], v[114:115]
	v_pk_fma_f32 v[126:127], v[110:111], v[226:227], v[116:117]
	v_cvt_f32_f16_e32 v110, v223
	v_cvt_f32_f16_sdwa v111, v223 dst_sel:DWORD dst_unused:UNUSED_PAD src0_sel:WORD_1
	v_cvt_f32_f16_e32 v112, v222
	v_cvt_f32_f16_sdwa v113, v222 dst_sel:DWORD dst_unused:UNUSED_PAD src0_sel:WORD_1
	v_pk_mul_f32 v[110:111], v[110:111], s[90:91] op_sel_hi:[1, 0]
	v_pk_mul_f32 v[112:113], v[112:113], s[90:91] op_sel_hi:[1, 0]
	v_pk_fma_f32 v[124:125], v[104:105], v[228:229], v[110:111]
	v_pk_fma_f32 v[122:123], v[102:103], v[226:227], v[112:113]
	v_cvt_f32_f16_e32 v102, v221
	v_cvt_f32_f16_sdwa v103, v221 dst_sel:DWORD dst_unused:UNUSED_PAD src0_sel:WORD_1
	v_cvt_f32_f16_e32 v104, v220
	v_cvt_f32_f16_sdwa v105, v220 dst_sel:DWORD dst_unused:UNUSED_PAD src0_sel:WORD_1
	v_pk_mul_f32 v[102:103], v[102:103], s[90:91] op_sel_hi:[1, 0]
	v_pk_mul_f32 v[104:105], v[104:105], s[90:91] op_sel_hi:[1, 0]
	v_pk_fma_f32 v[120:121], v[96:97], v[228:229], v[102:103]
	v_pk_fma_f32 v[118:119], v[94:95], v[226:227], v[104:105]
	v_cvt_f32_f16_e32 v94, v219
	v_cvt_f32_f16_sdwa v95, v219 dst_sel:DWORD dst_unused:UNUSED_PAD src0_sel:WORD_1
	v_cvt_f32_f16_e32 v96, v218
	v_cvt_f32_f16_sdwa v97, v218 dst_sel:DWORD dst_unused:UNUSED_PAD src0_sel:WORD_1
	v_pk_mul_f32 v[94:95], v[94:95], s[90:91] op_sel_hi:[1, 0]
	v_pk_mul_f32 v[96:97], v[96:97], s[90:91] op_sel_hi:[1, 0]
	v_pk_fma_f32 v[116:117], v[76:77], v[228:229], v[94:95]
	v_pk_fma_f32 v[114:115], v[74:75], v[226:227], v[96:97]
	v_cvt_f32_f16_e32 v94, v216
	v_cvt_f32_f16_sdwa v95, v216 dst_sel:DWORD dst_unused:UNUSED_PAD src0_sel:WORD_1
	v_cvt_f32_f16_e32 v96, v217
	v_cvt_f32_f16_sdwa v97, v217 dst_sel:DWORD dst_unused:UNUSED_PAD src0_sel:WORD_1
	v_pk_mul_f32 v[76:77], v[234:235], 0.5 op_sel_hi:[1, 0]
	v_pk_mul_f32 v[74:75], v[232:233], 0.5 op_sel_hi:[1, 0]
	v_pk_mul_f32 v[102:103], v[108:109], v[76:77]
	v_pk_mul_f32 v[104:105], v[106:107], v[74:75]
	v_pk_fma_f32 v[112:113], v[96:97], s[90:91], v[102:103] op_sel_hi:[1, 0, 1]
	v_pk_fma_f32 v[110:111], v[94:95], s[90:91], v[104:105] op_sel_hi:[1, 0, 1]
	v_cvt_f32_f16_e32 v94, v214
	v_cvt_f32_f16_sdwa v95, v214 dst_sel:DWORD dst_unused:UNUSED_PAD src0_sel:WORD_1
	v_cvt_f32_f16_e32 v96, v215
	v_cvt_f32_f16_sdwa v97, v215 dst_sel:DWORD dst_unused:UNUSED_PAD src0_sel:WORD_1
	v_pk_mul_f32 v[100:101], v[100:101], v[76:77]
	v_pk_mul_f32 v[98:99], v[98:99], v[74:75]
	v_pk_mul_f32 v[92:93], v[92:93], v[76:77]
	v_pk_fma_f32 v[108:109], v[96:97], s[90:91], v[100:101] op_sel_hi:[1, 0, 1]
	v_pk_fma_f32 v[106:107], v[94:95], s[90:91], v[98:99] op_sel_hi:[1, 0, 1]
	v_cvt_f32_f16_e32 v94, v212
	v_cvt_f32_f16_sdwa v95, v212 dst_sel:DWORD dst_unused:UNUSED_PAD src0_sel:WORD_1
	v_cvt_f32_f16_e32 v96, v213
	v_cvt_f32_f16_sdwa v97, v213 dst_sel:DWORD dst_unused:UNUSED_PAD src0_sel:WORD_1
	v_pk_mul_f32 v[90:91], v[90:91], v[74:75]
	v_pk_mul_f32 v[80:81], v[80:81], v[76:77]
	v_pk_fma_f32 v[102:103], v[94:95], s[90:91], v[90:91] op_sel_hi:[1, 0, 1]
	v_pk_fma_f32 v[104:105], v[96:97], s[90:91], v[92:93] op_sel_hi:[1, 0, 1]
	v_cvt_f32_f16_e32 v90, v210
	v_cvt_f32_f16_sdwa v91, v210 dst_sel:DWORD dst_unused:UNUSED_PAD src0_sel:WORD_1
	v_cvt_f32_f16_e32 v92, v211
	v_cvt_f32_f16_sdwa v93, v211 dst_sel:DWORD dst_unused:UNUSED_PAD src0_sel:WORD_1
	v_pk_mul_f32 v[78:79], v[78:79], v[74:75]
	v_pk_mul_f32 v[72:73], v[72:73], v[76:77]
	v_pk_fma_f32 v[98:99], v[90:91], s[90:91], v[78:79] op_sel_hi:[1, 0, 1]
	v_pk_fma_f32 v[100:101], v[92:93], s[90:91], v[80:81] op_sel_hi:[1, 0, 1]
	v_cvt_f32_f16_e32 v78, v208
	v_cvt_f32_f16_sdwa v79, v208 dst_sel:DWORD dst_unused:UNUSED_PAD src0_sel:WORD_1
	v_cvt_f32_f16_e32 v80, v209
	v_cvt_f32_f16_sdwa v81, v209 dst_sel:DWORD dst_unused:UNUSED_PAD src0_sel:WORD_1
	v_pk_mul_f32 v[70:71], v[70:71], v[74:75]
	v_pk_mul_f32 v[64:65], v[64:65], v[76:77]
	v_pk_fma_f32 v[94:95], v[78:79], s[90:91], v[70:71] op_sel_hi:[1, 0, 1]
	v_pk_fma_f32 v[96:97], v[80:81], s[90:91], v[72:73] op_sel_hi:[1, 0, 1]
	v_cvt_f32_f16_e32 v70, v206
	v_cvt_f32_f16_sdwa v71, v206 dst_sel:DWORD dst_unused:UNUSED_PAD src0_sel:WORD_1
	v_cvt_f32_f16_e32 v72, v207
	v_cvt_f32_f16_sdwa v73, v207 dst_sel:DWORD dst_unused:UNUSED_PAD src0_sel:WORD_1
	v_pk_mul_f32 v[62:63], v[62:63], v[74:75]
	v_pk_mul_f32 v[60:61], v[60:61], v[76:77]
	v_pk_fma_f32 v[90:91], v[70:71], s[90:91], v[62:63] op_sel_hi:[1, 0, 1]
	v_pk_fma_f32 v[92:93], v[72:73], s[90:91], v[64:65] op_sel_hi:[1, 0, 1]
	v_cvt_f32_f16_e32 v62, v204
	v_cvt_f32_f16_sdwa v63, v204 dst_sel:DWORD dst_unused:UNUSED_PAD src0_sel:WORD_1
	v_cvt_f32_f16_e32 v64, v205
	v_cvt_f32_f16_sdwa v65, v205 dst_sel:DWORD dst_unused:UNUSED_PAD src0_sel:WORD_1
	v_pk_mul_f32 v[58:59], v[58:59], v[74:75]
	v_pk_mul_f32 v[52:53], v[52:53], v[76:77]
	v_pk_fma_f32 v[78:79], v[62:63], s[90:91], v[58:59] op_sel_hi:[1, 0, 1]
	v_pk_fma_f32 v[80:81], v[64:65], s[90:91], v[60:61] op_sel_hi:[1, 0, 1]
	v_cvt_f32_f16_e32 v58, v202
	v_cvt_f32_f16_sdwa v59, v202 dst_sel:DWORD dst_unused:UNUSED_PAD src0_sel:WORD_1
	v_cvt_f32_f16_e32 v60, v203
	v_cvt_f32_f16_sdwa v61, v203 dst_sel:DWORD dst_unused:UNUSED_PAD src0_sel:WORD_1
	v_pk_mul_f32 v[50:51], v[50:51], v[74:75]
	v_pk_fma_f32 v[76:77], v[60:61], s[90:91], v[52:53] op_sel_hi:[1, 0, 1]
	v_pk_fma_f32 v[74:75], v[58:59], s[90:91], v[50:51] op_sel_hi:[1, 0, 1]
	s_nop 0
	v_pk_mul_f32 v[204:205], v[238:239], 0.5 op_sel_hi:[1, 0]
	v_pk_mul_f32 v[202:203], v[236:237], 0.5 op_sel_hi:[1, 0]
	v_cvt_f32_f16_e32 v50, v200
	v_cvt_f32_f16_sdwa v51, v200 dst_sel:DWORD dst_unused:UNUSED_PAD src0_sel:WORD_1
	v_cvt_f32_f16_e32 v52, v201
	v_cvt_f32_f16_sdwa v53, v201 dst_sel:DWORD dst_unused:UNUSED_PAD src0_sel:WORD_1
	v_pk_mul_f32 v[58:59], v[68:69], v[204:205]
	v_pk_mul_f32 v[60:61], v[66:67], v[202:203]
	v_pk_mul_f32 v[56:57], v[56:57], v[204:205]
	v_pk_fma_f32 v[72:73], v[52:53], s[90:91], v[58:59] op_sel_hi:[1, 0, 1]
	v_pk_fma_f32 v[70:71], v[50:51], s[90:91], v[60:61] op_sel_hi:[1, 0, 1]
	v_cvt_f32_f16_e32 v50, v176
	v_cvt_f32_f16_sdwa v51, v176 dst_sel:DWORD dst_unused:UNUSED_PAD src0_sel:WORD_1
	v_cvt_f32_f16_e32 v52, v177
	v_cvt_f32_f16_sdwa v53, v177 dst_sel:DWORD dst_unused:UNUSED_PAD src0_sel:WORD_1
	v_pk_mul_f32 v[54:55], v[54:55], v[202:203]
	v_pk_mul_f32 v[48:49], v[48:49], v[204:205]
	v_pk_fma_f32 v[66:67], v[50:51], s[90:91], v[54:55] op_sel_hi:[1, 0, 1]
	v_pk_fma_f32 v[68:69], v[52:53], s[90:91], v[56:57] op_sel_hi:[1, 0, 1]
	v_cvt_f32_f16_e32 v50, v174
	v_cvt_f32_f16_sdwa v51, v174 dst_sel:DWORD dst_unused:UNUSED_PAD src0_sel:WORD_1
	v_cvt_f32_f16_e32 v52, v175
	v_cvt_f32_f16_sdwa v53, v175 dst_sel:DWORD dst_unused:UNUSED_PAD src0_sel:WORD_1
	v_pk_mul_f32 v[46:47], v[46:47], v[202:203]
	v_pk_mul_f32 v[44:45], v[44:45], v[204:205]
	v_pk_fma_f32 v[62:63], v[50:51], s[90:91], v[46:47] op_sel_hi:[1, 0, 1]
	v_pk_fma_f32 v[64:65], v[52:53], s[90:91], v[48:49] op_sel_hi:[1, 0, 1]
	v_cvt_f32_f16_e32 v46, v172
	v_cvt_f32_f16_sdwa v47, v172 dst_sel:DWORD dst_unused:UNUSED_PAD src0_sel:WORD_1
	v_cvt_f32_f16_e32 v48, v173
	v_cvt_f32_f16_sdwa v49, v173 dst_sel:DWORD dst_unused:UNUSED_PAD src0_sel:WORD_1
	v_pk_mul_f32 v[42:43], v[42:43], v[202:203]
	v_pk_mul_f32 v[40:41], v[40:41], v[204:205]
	v_pk_fma_f32 v[58:59], v[46:47], s[90:91], v[42:43] op_sel_hi:[1, 0, 1]
	v_pk_fma_f32 v[60:61], v[48:49], s[90:91], v[44:45] op_sel_hi:[1, 0, 1]
	v_cvt_f32_f16_e32 v42, v170
	v_cvt_f32_f16_sdwa v43, v170 dst_sel:DWORD dst_unused:UNUSED_PAD src0_sel:WORD_1
	v_cvt_f32_f16_e32 v44, v171
	v_cvt_f32_f16_sdwa v45, v171 dst_sel:DWORD dst_unused:UNUSED_PAD src0_sel:WORD_1
	v_pk_mul_f32 v[38:39], v[38:39], v[202:203]
	v_pk_mul_f32 v[36:37], v[36:37], v[204:205]
	v_pk_fma_f32 v[54:55], v[42:43], s[90:91], v[38:39] op_sel_hi:[1, 0, 1]
	v_pk_fma_f32 v[56:57], v[44:45], s[90:91], v[40:41] op_sel_hi:[1, 0, 1]
	v_cvt_f32_f16_e32 v38, v168
	v_cvt_f32_f16_sdwa v39, v168 dst_sel:DWORD dst_unused:UNUSED_PAD src0_sel:WORD_1
	v_cvt_f32_f16_e32 v40, v169
	v_cvt_f32_f16_sdwa v41, v169 dst_sel:DWORD dst_unused:UNUSED_PAD src0_sel:WORD_1
	v_pk_mul_f32 v[34:35], v[34:35], v[202:203]
	v_pk_mul_f32 v[32:33], v[32:33], v[204:205]
	v_pk_fma_f32 v[50:51], v[38:39], s[90:91], v[34:35] op_sel_hi:[1, 0, 1]
	v_pk_fma_f32 v[52:53], v[40:41], s[90:91], v[36:37] op_sel_hi:[1, 0, 1]
	v_cvt_f32_f16_e32 v34, v166
	v_cvt_f32_f16_sdwa v35, v166 dst_sel:DWORD dst_unused:UNUSED_PAD src0_sel:WORD_1
	v_cvt_f32_f16_e32 v36, v167
	v_cvt_f32_f16_sdwa v37, v167 dst_sel:DWORD dst_unused:UNUSED_PAD src0_sel:WORD_1
	v_pk_mul_f32 v[30:31], v[30:31], v[202:203]
	v_pk_mul_f32 v[24:25], v[24:25], v[204:205]
	v_pk_fma_f32 v[46:47], v[34:35], s[90:91], v[30:31] op_sel_hi:[1, 0, 1]
	v_pk_fma_f32 v[48:49], v[36:37], s[90:91], v[32:33] op_sel_hi:[1, 0, 1]
	v_cvt_f32_f16_e32 v30, v164
	v_cvt_f32_f16_sdwa v31, v164 dst_sel:DWORD dst_unused:UNUSED_PAD src0_sel:WORD_1
	v_cvt_f32_f16_e32 v32, v165
	v_cvt_f32_f16_sdwa v33, v165 dst_sel:DWORD dst_unused:UNUSED_PAD src0_sel:WORD_1
	v_pk_mul_f32 v[22:23], v[22:23], v[202:203]
	v_pk_fma_f32 v[44:45], v[32:33], s[90:91], v[24:25] op_sel_hi:[1, 0, 1]
	v_pk_fma_f32 v[42:43], v[30:31], s[90:91], v[22:23] op_sel_hi:[1, 0, 1]
	s_nop 0
	v_mov_b32_e32 v168, v110
	v_mov_b32_e32 v169, v113
	v_add_f32_e32 v170, v72, v73
	v_pk_mul_f32 v[166:167], v[242:243], 0.5 op_sel_hi:[1, 0]
	v_pk_mul_f32 v[164:165], v[240:241], 0.5 op_sel_hi:[1, 0]
	v_cvt_f32_f16_e32 v22, v160
	v_cvt_f32_f16_sdwa v23, v160 dst_sel:DWORD dst_unused:UNUSED_PAD src0_sel:WORD_1
	v_cvt_f32_f16_e32 v24, v161
	v_cvt_f32_f16_sdwa v25, v161 dst_sel:DWORD dst_unused:UNUSED_PAD src0_sel:WORD_1
	v_pk_mul_f32 v[30:31], v[88:89], v[166:167]
	v_pk_mul_f32 v[32:33], v[86:87], v[164:165]
	v_pk_mul_f32 v[34:35], v[82:83], v[164:165]
	v_pk_fma_f32 v[40:41], v[24:25], s[90:91], v[30:31] op_sel_hi:[1, 0, 1]
	v_pk_fma_f32 v[38:39], v[22:23], s[90:91], v[32:33] op_sel_hi:[1, 0, 1]
	v_cvt_f32_f16_e32 v22, v158
	v_cvt_f32_f16_sdwa v23, v158 dst_sel:DWORD dst_unused:UNUSED_PAD src0_sel:WORD_1
	v_cvt_f32_f16_e32 v24, v159
	v_cvt_f32_f16_sdwa v25, v159 dst_sel:DWORD dst_unused:UNUSED_PAD src0_sel:WORD_1
	v_pk_mul_f32 v[30:31], v[84:85], v[166:167]
	v_pk_mul_f32 v[28:29], v[28:29], v[166:167]
	v_pk_mul_f32 v[26:27], v[26:27], v[164:165]
	v_pk_fma_f32 v[32:33], v[24:25], s[90:91], v[30:31] op_sel_hi:[1, 0, 1]
	v_pk_fma_f32 v[30:31], v[22:23], s[90:91], v[34:35] op_sel_hi:[1, 0, 1]
	v_cvt_f32_f16_e32 v22, v156
	v_cvt_f32_f16_sdwa v23, v156 dst_sel:DWORD dst_unused:UNUSED_PAD src0_sel:WORD_1
	v_cvt_f32_f16_e32 v24, v157
	v_cvt_f32_f16_sdwa v25, v157 dst_sel:DWORD dst_unused:UNUSED_PAD src0_sel:WORD_1
	v_pk_mul_f32 v[20:21], v[20:21], v[166:167]
	v_pk_fma_f32 v[34:35], v[22:23], s[90:91], v[26:27] op_sel_hi:[1, 0, 1]
	v_cvt_f32_f16_e32 v22, v154
	v_pk_fma_f32 v[36:37], v[24:25], s[90:91], v[28:29] op_sel_hi:[1, 0, 1]
	v_cvt_f32_f16_sdwa v23, v154 dst_sel:DWORD dst_unused:UNUSED_PAD src0_sel:WORD_1
	v_cvt_f32_f16_e32 v24, v155
	v_cvt_f32_f16_sdwa v25, v155 dst_sel:DWORD dst_unused:UNUSED_PAD src0_sel:WORD_1
	v_pk_mul_f32 v[18:19], v[18:19], v[164:165]
	v_pk_mul_f32 v[16:17], v[16:17], v[166:167]
	v_pk_fma_f32 v[26:27], v[22:23], s[90:91], v[18:19] op_sel_hi:[1, 0, 1]
	v_pk_fma_f32 v[28:29], v[24:25], s[90:91], v[20:21] op_sel_hi:[1, 0, 1]
	v_cvt_f32_f16_e32 v18, v152
	v_cvt_f32_f16_sdwa v19, v152 dst_sel:DWORD dst_unused:UNUSED_PAD src0_sel:WORD_1
	v_cvt_f32_f16_e32 v20, v153
	v_cvt_f32_f16_sdwa v21, v153 dst_sel:DWORD dst_unused:UNUSED_PAD src0_sel:WORD_1
	v_pk_mul_f32 v[14:15], v[14:15], v[164:165]
	v_pk_mul_f32 v[12:13], v[12:13], v[166:167]
	v_pk_fma_f32 v[22:23], v[18:19], s[90:91], v[14:15] op_sel_hi:[1, 0, 1]
	v_pk_fma_f32 v[24:25], v[20:21], s[90:91], v[16:17] op_sel_hi:[1, 0, 1]
	v_cvt_f32_f16_e32 v14, v150
	v_cvt_f32_f16_sdwa v15, v150 dst_sel:DWORD dst_unused:UNUSED_PAD src0_sel:WORD_1
	v_cvt_f32_f16_e32 v16, v151
	v_cvt_f32_f16_sdwa v17, v151 dst_sel:DWORD dst_unused:UNUSED_PAD src0_sel:WORD_1
	v_pk_mul_f32 v[10:11], v[10:11], v[164:165]
	v_pk_mul_f32 v[8:9], v[8:9], v[166:167]
	v_pk_fma_f32 v[18:19], v[14:15], s[90:91], v[10:11] op_sel_hi:[1, 0, 1]
	v_pk_fma_f32 v[20:21], v[16:17], s[90:91], v[12:13] op_sel_hi:[1, 0, 1]
	v_cvt_f32_f16_e32 v10, v148
	v_cvt_f32_f16_sdwa v11, v148 dst_sel:DWORD dst_unused:UNUSED_PAD src0_sel:WORD_1
	v_cvt_f32_f16_e32 v12, v149
	v_cvt_f32_f16_sdwa v13, v149 dst_sel:DWORD dst_unused:UNUSED_PAD src0_sel:WORD_1
	v_pk_mul_f32 v[6:7], v[6:7], v[164:165]
	v_pk_mul_f32 v[4:5], v[4:5], v[166:167]
	v_pk_fma_f32 v[14:15], v[10:11], s[90:91], v[6:7] op_sel_hi:[1, 0, 1]
	v_pk_fma_f32 v[16:17], v[12:13], s[90:91], v[8:9] op_sel_hi:[1, 0, 1]
	v_cvt_f32_f16_e32 v6, v146
	v_cvt_f32_f16_sdwa v7, v146 dst_sel:DWORD dst_unused:UNUSED_PAD src0_sel:WORD_1
	v_cvt_f32_f16_e32 v8, v147
	v_cvt_f32_f16_sdwa v9, v147 dst_sel:DWORD dst_unused:UNUSED_PAD src0_sel:WORD_1
	v_pk_mul_f32 v[2:3], v[2:3], v[164:165]
	v_pk_fma_f32 v[4:5], v[8:9], s[90:91], v[4:5] op_sel_hi:[1, 0, 1]
	v_pk_fma_f32 v[2:3], v[6:7], s[90:91], v[2:3] op_sel_hi:[1, 0, 1]
	s_nop 0
	v_lshl_add_u64 v[6:7], s[8:9], 0, v[162:163]
	v_lshl_add_u64 v[10:11], s[6:7], 0, v[162:163]
	global_load_dwordx4 v[158:161], v[6:7], off
	global_load_dwordx4 v[162:165], v[10:11], off
	global_load_dwordx4 v[146:149], v[6:7], off offset:64
	global_load_dwordx4 v[150:153], v[10:11], off offset:64
	global_load_dwordx4 v[82:85], v[6:7], off offset:512
	global_load_dwordx4 v[86:89], v[10:11], off offset:512
	s_nop 0
	global_load_dwordx4 v[6:9], v[6:7], off offset:576
	s_nop 0
	global_load_dwordx4 v[10:13], v[10:11], off offset:576
	v_and_b32_e32 v155, 64, v249
	v_xor_b32_e32 v154, 16, v249
	v_add_u32_e32 v155, 64, v155
	v_cmp_lt_i32_e32 vcc, v154, v155
	v_xor_b32_e32 v156, 32, v249
	v_mov_b32_e32 v157, v144
	v_cndmask_b32_e32 v154, v249, v154, vcc
	v_cmp_lt_i32_e32 vcc, v156, v155
	v_mov_b32_e32 v166, v142
	v_mov_b32_e32 v167, v145
	v_cndmask_b32_e32 v155, v249, v156, vcc
	v_mov_b32_e32 v156, v143
	v_pk_add_f32 v[156:157], v[156:157], v[166:167]
	v_mov_b32_e32 v166, v111
	v_mov_b32_e32 v167, v112
	v_pk_add_f32 v[166:167], v[166:167], v[168:169]
	v_add_f32_e32 v156, v156, v157
	v_pk_add_f32 v[166:167], v[166:167], v[166:167] op_sel:[0,1] op_sel_hi:[1,0]
	v_add_f32_e32 v156, 0, v156
	v_add_f32_e32 v168, v70, v71
	v_mov_b32_e32 v157, v38
	v_mov_b32_e32 v167, v39
	v_mov_b32_e32 v169, v40
	v_mov_b32_e32 v171, v41
	v_pk_add_f32 v[156:157], v[156:157], v[166:167]
	v_pk_add_f32 v[166:167], v[168:169], v[170:171]
	v_lshlrev_b32_e32 v154, 2, v154
	v_pk_add_f32 v[156:157], v[156:157], v[166:167]
	v_lshlrev_b32_e32 v155, 2, v155
	v_add_f32_e32 v156, v156, v157
	v_mov_b32_e32 v157, v156
	s_nop 1
	v_permlane16_swap_b32_e32 v157, v156
	v_cmp_gt_u32_e32 vcc, 16, v0
	s_waitcnt lgkmcnt(0)
	v_add_f32_e32 v156, v156, v157
	v_mov_b32_e32 v157, v156
	s_nop 1
	v_permlane32_swap_b32_e32 v157, v156
	s_waitcnt lgkmcnt(0)
	v_add_f32_e32 v156, v156, v157
	v_fmamk_f32 v166, v156, 0xbc800000, v145
	v_fmamk_f32 v168, v156, 0xbc800000, v143
	v_fmamk_f32 v157, v156, 0xbc800000, v144
	v_fmamk_f32 v167, v156, 0xbc800000, v142
	v_mul_f32_e32 v168, v168, v168
	v_mul_f32_e32 v166, v166, v166
	v_fmac_f32_e32 v168, v167, v167
	v_fmac_f32_e32 v166, v157, v157
	v_fmamk_f32 v167, v156, 0xbc800000, v113
	v_fmamk_f32 v169, v156, 0xbc800000, v111
	v_add_f32_e32 v157, v168, v166
	v_fmamk_f32 v166, v156, 0xbc800000, v112
	v_fmamk_f32 v168, v156, 0xbc800000, v110
	v_mul_f32_e32 v169, v169, v169
	v_mul_f32_e32 v167, v167, v167
	v_fmac_f32_e32 v169, v168, v168
	v_fmac_f32_e32 v167, v166, v166
	v_add_f32_e32 v166, v169, v167
	v_fmamk_f32 v167, v156, 0xbc800000, v73
	v_fmamk_f32 v169, v156, 0xbc800000, v71
	v_add_f32_e32 v157, v157, v166
	v_fmamk_f32 v166, v156, 0xbc800000, v72
	v_fmamk_f32 v168, v156, 0xbc800000, v70
	v_mul_f32_e32 v169, v169, v169
	v_mul_f32_e32 v167, v167, v167
	v_fmac_f32_e32 v169, v168, v168
	v_fmac_f32_e32 v167, v166, v166
	v_add_f32_e32 v166, v169, v167
	v_fmamk_f32 v167, v156, 0xbc800000, v41
	v_fmamk_f32 v169, v156, 0xbc800000, v39
	v_add_f32_e32 v157, v166, v157
	v_fmamk_f32 v166, v156, 0xbc800000, v40
	v_fmamk_f32 v168, v156, 0xbc800000, v38
	v_mul_f32_e32 v169, v169, v169
	v_mul_f32_e32 v167, v167, v167
	v_fmac_f32_e32 v169, v168, v168
	v_fmac_f32_e32 v167, v166, v166
	v_add_f32_e32 v166, v169, v167
	v_add_f32_e32 v157, v166, v157
	v_mov_b32_e32 v166, v157
	s_nop 1
	v_permlane16_swap_b32_e32 v166, v157
	s_waitcnt lgkmcnt(0)
	v_add_f32_e32 v157, v157, v166
	v_mov_b32_e32 v166, v157
	s_nop 1
	v_permlane32_swap_b32_e32 v166, v157
	s_and_saveexec_b64 s[6:7], vcc
	s_cbranch_execz .LBB0_335
	s_lshl_b32 s8, s52, 11
	s_add_i32 s8, s2, s8
	v_mul_f32_e32 v156, 0x3c800000, v156
	v_lshl_add_u32 v167, v0, 5, s8
	s_waitcnt lgkmcnt(0)
	v_add_f32_e32 v157, v157, v166
	ds_write_b64 v167, v[156:157]
.LBB0_335:
	s_or_b64 exec, exec, s[6:7]
	v_mov_b32_e32 v156, v139
	v_mov_b32_e32 v157, v140
	s_waitcnt lgkmcnt(0)
	v_mov_b32_e32 v166, v138
	v_mov_b32_e32 v167, v141
	v_pk_add_f32 v[156:157], v[156:157], v[166:167]
	v_mov_b32_e32 v166, v107
	v_mov_b32_e32 v167, v108
	v_mov_b32_e32 v168, v106
	v_mov_b32_e32 v169, v109
	v_pk_add_f32 v[166:167], v[166:167], v[168:169]
	v_add_f32_e32 v156, v156, v157
	v_pk_add_f32 v[166:167], v[166:167], v[166:167] op_sel:[0,1] op_sel_hi:[1,0]
	v_add_f32_e32 v156, 0, v156
	v_add_f32_e32 v168, v66, v67
	v_add_f32_e32 v170, v68, v69
	v_mov_b32_e32 v157, v30
	v_mov_b32_e32 v167, v31
	v_mov_b32_e32 v169, v32
	v_mov_b32_e32 v171, v33
	v_pk_add_f32 v[156:157], v[156:157], v[166:167]
	v_pk_add_f32 v[166:167], v[168:169], v[170:171]
	s_nop 0
	v_pk_add_f32 v[156:157], v[156:157], v[166:167]
	s_nop 0
	v_add_f32_e32 v156, v156, v157
	v_mov_b32_e32 v157, v156
	s_nop 1
	v_permlane16_swap_b32_e32 v157, v156
	s_waitcnt lgkmcnt(0)
	v_add_f32_e32 v156, v156, v157
	v_mov_b32_e32 v157, v156
	s_nop 1
	v_permlane32_swap_b32_e32 v157, v156
	s_waitcnt lgkmcnt(0)
	v_add_f32_e32 v156, v156, v157
	v_fmamk_f32 v166, v156, 0xbc800000, v141
	v_fmamk_f32 v168, v156, 0xbc800000, v139
	v_fmamk_f32 v157, v156, 0xbc800000, v140
	v_fmamk_f32 v167, v156, 0xbc800000, v138
	v_mul_f32_e32 v168, v168, v168
	v_mul_f32_e32 v166, v166, v166
	v_fmac_f32_e32 v168, v167, v167
	v_fmac_f32_e32 v166, v157, v157
	v_fmamk_f32 v167, v156, 0xbc800000, v109
	v_fmamk_f32 v169, v156, 0xbc800000, v107
	v_add_f32_e32 v157, v168, v166
	v_fmamk_f32 v166, v156, 0xbc800000, v108
	v_fmamk_f32 v168, v156, 0xbc800000, v106
	v_mul_f32_e32 v169, v169, v169
	v_mul_f32_e32 v167, v167, v167
	v_fmac_f32_e32 v169, v168, v168
	v_fmac_f32_e32 v167, v166, v166
	v_add_f32_e32 v166, v169, v167
	v_fmamk_f32 v167, v156, 0xbc800000, v69
	v_fmamk_f32 v169, v156, 0xbc800000, v67
	v_add_f32_e32 v157, v157, v166
	v_fmamk_f32 v166, v156, 0xbc800000, v68
	v_fmamk_f32 v168, v156, 0xbc800000, v66
	v_mul_f32_e32 v169, v169, v169
	v_mul_f32_e32 v167, v167, v167
	v_fmac_f32_e32 v169, v168, v168
	v_fmac_f32_e32 v167, v166, v166
	v_add_f32_e32 v166, v169, v167
	v_fmamk_f32 v167, v156, 0xbc800000, v33
	v_fmamk_f32 v169, v156, 0xbc800000, v31
	v_add_f32_e32 v157, v166, v157
	v_fmamk_f32 v166, v156, 0xbc800000, v32
	v_fmamk_f32 v168, v156, 0xbc800000, v30
	v_mul_f32_e32 v169, v169, v169
	v_mul_f32_e32 v167, v167, v167
	v_fmac_f32_e32 v169, v168, v168
	v_fmac_f32_e32 v167, v166, v166
	v_add_f32_e32 v166, v169, v167
	v_add_f32_e32 v157, v166, v157
	v_mov_b32_e32 v166, v157
	s_nop 1
	v_permlane16_swap_b32_e32 v166, v157
	s_waitcnt lgkmcnt(0)
	v_add_f32_e32 v157, v157, v166
	v_mov_b32_e32 v166, v157
	s_nop 1
	v_permlane32_swap_b32_e32 v166, v157
	s_and_saveexec_b64 s[6:7], vcc
	v_readlane_b32 s70, v254, 56
	v_readlane_b32 s91, v254, 63
	v_readlane_b32 s71, v254, 57
	v_readlane_b32 s92, v253, 0
	v_readlane_b32 s38, v254, 58
	v_readlane_b32 s93, v253, 1
	v_readlane_b32 s95, v253, 2
	v_readlane_b32 s51, v254, 60
	v_readlane_b32 s76, v254, 61
	v_readlane_b32 s83, v254, 62
	s_movk_i32 s59, 0x48
	s_movk_i32 s79, 0x60
	s_mov_b32 s96, 0xf800000
	s_movk_i32 s65, 0xff5d
	s_movk_i32 s64, 0xff7c
	v_readlane_b32 s33, v253, 15
	s_movk_i32 s50, 0x57
	v_readlane_b32 s39, v254, 59
	s_cbranch_execz .LBB0_337
	s_lshl_b32 s8, s52, 11
	s_add_i32 s8, s2, s8
	v_mul_f32_e32 v156, 0x3c800000, v156
	v_lshl_add_u32 v167, v0, 5, s8
	s_waitcnt lgkmcnt(0)
	v_add_f32_e32 v157, v157, v166
	ds_write_b64 v167, v[156:157] offset:512
.LBB0_337:
	s_or_b64 exec, exec, s[6:7]
	v_mov_b32_e32 v156, v135
	v_mov_b32_e32 v157, v136
	s_waitcnt lgkmcnt(0)
	v_mov_b32_e32 v166, v134
	v_mov_b32_e32 v167, v137
	v_pk_add_f32 v[156:157], v[156:157], v[166:167]
	v_mov_b32_e32 v166, v103
	v_mov_b32_e32 v167, v104
	v_mov_b32_e32 v168, v102
	v_mov_b32_e32 v169, v105
	v_pk_add_f32 v[166:167], v[166:167], v[168:169]
	v_add_f32_e32 v156, v156, v157
	v_pk_add_f32 v[166:167], v[166:167], v[166:167] op_sel:[0,1] op_sel_hi:[1,0]
	v_add_f32_e32 v156, 0, v156
	v_add_f32_e32 v168, v62, v63
	v_add_f32_e32 v170, v64, v65
	v_mov_b32_e32 v157, v34
	v_mov_b32_e32 v167, v35
	v_mov_b32_e32 v169, v36
	v_mov_b32_e32 v171, v37
	v_pk_add_f32 v[156:157], v[156:157], v[166:167]
	v_pk_add_f32 v[166:167], v[168:169], v[170:171]
	s_nop 0
	v_pk_add_f32 v[156:157], v[156:157], v[166:167]
	s_nop 0
	v_add_f32_e32 v156, v156, v157
	v_mov_b32_e32 v157, v156
	s_nop 1
	v_permlane16_swap_b32_e32 v157, v156
	s_waitcnt lgkmcnt(0)
	v_add_f32_e32 v156, v156, v157
	v_mov_b32_e32 v157, v156
	s_nop 1
	v_permlane32_swap_b32_e32 v157, v156
	s_waitcnt lgkmcnt(0)
	v_add_f32_e32 v156, v156, v157
	v_fmamk_f32 v166, v156, 0xbc800000, v137
	v_fmamk_f32 v168, v156, 0xbc800000, v135
	v_fmamk_f32 v157, v156, 0xbc800000, v136
	v_fmamk_f32 v167, v156, 0xbc800000, v134
	v_mul_f32_e32 v168, v168, v168
	v_mul_f32_e32 v166, v166, v166
	v_fmac_f32_e32 v168, v167, v167
	v_fmac_f32_e32 v166, v157, v157
	v_fmamk_f32 v167, v156, 0xbc800000, v105
	v_fmamk_f32 v169, v156, 0xbc800000, v103
	v_add_f32_e32 v157, v168, v166
	v_fmamk_f32 v166, v156, 0xbc800000, v104
	v_fmamk_f32 v168, v156, 0xbc800000, v102
	v_mul_f32_e32 v169, v169, v169
	v_mul_f32_e32 v167, v167, v167
	v_fmac_f32_e32 v169, v168, v168
	v_fmac_f32_e32 v167, v166, v166
	v_add_f32_e32 v166, v169, v167
	v_fmamk_f32 v167, v156, 0xbc800000, v65
	v_fmamk_f32 v169, v156, 0xbc800000, v63
	v_add_f32_e32 v157, v157, v166
	v_fmamk_f32 v166, v156, 0xbc800000, v64
	v_fmamk_f32 v168, v156, 0xbc800000, v62
	v_mul_f32_e32 v169, v169, v169
	v_mul_f32_e32 v167, v167, v167
	v_fmac_f32_e32 v169, v168, v168
	v_fmac_f32_e32 v167, v166, v166
	v_add_f32_e32 v166, v169, v167
	v_fmamk_f32 v167, v156, 0xbc800000, v37
	v_fmamk_f32 v169, v156, 0xbc800000, v35
	v_add_f32_e32 v157, v166, v157
	v_fmamk_f32 v166, v156, 0xbc800000, v36
	v_fmamk_f32 v168, v156, 0xbc800000, v34
	v_mul_f32_e32 v169, v169, v169
	v_mul_f32_e32 v167, v167, v167
	v_fmac_f32_e32 v169, v168, v168
	v_fmac_f32_e32 v167, v166, v166
	v_add_f32_e32 v166, v169, v167
	v_add_f32_e32 v157, v166, v157
	v_mov_b32_e32 v166, v157
	s_nop 1
	v_permlane16_swap_b32_e32 v166, v157
	s_waitcnt lgkmcnt(0)
	v_add_f32_e32 v157, v157, v166
	v_mov_b32_e32 v166, v157
	s_nop 1
	v_permlane32_swap_b32_e32 v166, v157
	s_and_saveexec_b64 s[6:7], vcc
	s_cbranch_execz .LBB0_339
	s_lshl_b32 s8, s52, 11
	s_add_i32 s8, s2, s8
	v_mul_f32_e32 v156, 0x3c800000, v156
	v_lshl_add_u32 v167, v0, 5, s8
	s_waitcnt lgkmcnt(0)
	v_add_f32_e32 v157, v157, v166
	ds_write_b64 v167, v[156:157] offset:1024
.LBB0_339:
	s_or_b64 exec, exec, s[6:7]
	v_mov_b32_e32 v156, v131
	v_mov_b32_e32 v157, v132
	s_waitcnt lgkmcnt(0)
	v_mov_b32_e32 v166, v130
	v_mov_b32_e32 v167, v133
	v_pk_add_f32 v[156:157], v[156:157], v[166:167]
	v_mov_b32_e32 v166, v99
	v_mov_b32_e32 v167, v100
	v_mov_b32_e32 v168, v98
	v_mov_b32_e32 v169, v101
	v_pk_add_f32 v[166:167], v[166:167], v[168:169]
	v_add_f32_e32 v156, v156, v157
	v_pk_add_f32 v[166:167], v[166:167], v[166:167] op_sel:[0,1] op_sel_hi:[1,0]
	v_add_f32_e32 v156, 0, v156
	v_add_f32_e32 v168, v58, v59
	v_add_f32_e32 v170, v60, v61
	v_mov_b32_e32 v157, v26
	v_mov_b32_e32 v167, v27
	v_mov_b32_e32 v169, v28
	v_mov_b32_e32 v171, v29
	v_pk_add_f32 v[156:157], v[156:157], v[166:167]
	v_pk_add_f32 v[166:167], v[168:169], v[170:171]
	s_nop 0
	v_pk_add_f32 v[156:157], v[156:157], v[166:167]
	s_nop 0
	v_add_f32_e32 v156, v156, v157
	v_mov_b32_e32 v157, v156
	s_nop 1
	v_permlane16_swap_b32_e32 v157, v156
	s_waitcnt lgkmcnt(0)
	v_add_f32_e32 v156, v156, v157
	v_mov_b32_e32 v157, v156
	s_nop 1
	v_permlane32_swap_b32_e32 v157, v156
	s_waitcnt lgkmcnt(0)
	v_add_f32_e32 v156, v156, v157
	v_fmamk_f32 v166, v156, 0xbc800000, v133
	v_fmamk_f32 v168, v156, 0xbc800000, v131
	v_fmamk_f32 v157, v156, 0xbc800000, v132
	v_fmamk_f32 v167, v156, 0xbc800000, v130
	v_mul_f32_e32 v168, v168, v168
	v_mul_f32_e32 v166, v166, v166
	v_fmac_f32_e32 v168, v167, v167
	v_fmac_f32_e32 v166, v157, v157
	v_fmamk_f32 v167, v156, 0xbc800000, v101
	v_fmamk_f32 v169, v156, 0xbc800000, v99
	v_add_f32_e32 v157, v168, v166
	v_fmamk_f32 v166, v156, 0xbc800000, v100
	v_fmamk_f32 v168, v156, 0xbc800000, v98
	v_mul_f32_e32 v169, v169, v169
	v_mul_f32_e32 v167, v167, v167
	v_fmac_f32_e32 v169, v168, v168
	v_fmac_f32_e32 v167, v166, v166
	v_add_f32_e32 v166, v169, v167
	v_fmamk_f32 v167, v156, 0xbc800000, v61
	v_fmamk_f32 v169, v156, 0xbc800000, v59
	v_add_f32_e32 v157, v157, v166
	v_fmamk_f32 v166, v156, 0xbc800000, v60
	v_fmamk_f32 v168, v156, 0xbc800000, v58
	v_mul_f32_e32 v169, v169, v169
	v_mul_f32_e32 v167, v167, v167
	v_fmac_f32_e32 v169, v168, v168
	v_fmac_f32_e32 v167, v166, v166
	v_add_f32_e32 v166, v169, v167
	v_fmamk_f32 v167, v156, 0xbc800000, v29
	v_fmamk_f32 v169, v156, 0xbc800000, v27
	v_add_f32_e32 v157, v166, v157
	v_fmamk_f32 v166, v156, 0xbc800000, v28
	v_fmamk_f32 v168, v156, 0xbc800000, v26
	v_mul_f32_e32 v169, v169, v169
	v_mul_f32_e32 v167, v167, v167
	v_fmac_f32_e32 v169, v168, v168
	v_fmac_f32_e32 v167, v166, v166
	v_add_f32_e32 v166, v169, v167
	v_add_f32_e32 v157, v166, v157
	v_mov_b32_e32 v166, v157
	s_nop 1
	v_permlane16_swap_b32_e32 v166, v157
	s_waitcnt lgkmcnt(0)
	v_add_f32_e32 v157, v157, v166
	v_mov_b32_e32 v166, v157
	s_nop 1
	v_permlane32_swap_b32_e32 v166, v157
	s_and_saveexec_b64 s[6:7], vcc
	s_cbranch_execz .LBB0_341
	s_lshl_b32 s8, s52, 11
	s_add_i32 s8, s2, s8
	v_mul_f32_e32 v156, 0x3c800000, v156
	v_lshl_add_u32 v167, v0, 5, s8
	s_waitcnt lgkmcnt(0)
	v_add_f32_e32 v157, v157, v166
	ds_write_b64 v167, v[156:157] offset:1536
.LBB0_341:
	s_or_b64 exec, exec, s[6:7]
	v_mov_b32_e32 v156, v127
	v_mov_b32_e32 v157, v128
	s_waitcnt lgkmcnt(0)
	v_mov_b32_e32 v166, v126
	v_mov_b32_e32 v167, v129
	v_pk_add_f32 v[156:157], v[156:157], v[166:167]
	v_mov_b32_e32 v166, v95
	v_mov_b32_e32 v167, v96
	v_mov_b32_e32 v168, v94
	v_mov_b32_e32 v169, v97
	v_pk_add_f32 v[166:167], v[166:167], v[168:169]
	v_add_f32_e32 v156, v156, v157
	v_pk_add_f32 v[166:167], v[166:167], v[166:167] op_sel:[0,1] op_sel_hi:[1,0]
	v_add_f32_e32 v156, 0, v156
	v_add_f32_e32 v168, v54, v55
	v_add_f32_e32 v170, v56, v57
	v_mov_b32_e32 v157, v22
	v_mov_b32_e32 v167, v23
	v_mov_b32_e32 v169, v24
	v_mov_b32_e32 v171, v25
	v_pk_add_f32 v[156:157], v[156:157], v[166:167]
	v_pk_add_f32 v[166:167], v[168:169], v[170:171]
	s_nop 0
	v_pk_add_f32 v[156:157], v[156:157], v[166:167]
	s_nop 0
	v_add_f32_e32 v156, v156, v157
	v_mov_b32_e32 v157, v156
	s_nop 1
	v_permlane16_swap_b32_e32 v157, v156
	s_waitcnt lgkmcnt(0)
	v_add_f32_e32 v156, v156, v157
	v_mov_b32_e32 v157, v156
	s_nop 1
	v_permlane32_swap_b32_e32 v157, v156
	s_waitcnt lgkmcnt(0)
	v_add_f32_e32 v156, v156, v157
	v_fmamk_f32 v166, v156, 0xbc800000, v129
	v_fmamk_f32 v168, v156, 0xbc800000, v127
	v_fmamk_f32 v157, v156, 0xbc800000, v128
	v_fmamk_f32 v167, v156, 0xbc800000, v126
	v_mul_f32_e32 v168, v168, v168
	v_mul_f32_e32 v166, v166, v166
	v_fmac_f32_e32 v168, v167, v167
	v_fmac_f32_e32 v166, v157, v157
	v_fmamk_f32 v167, v156, 0xbc800000, v97
	v_fmamk_f32 v169, v156, 0xbc800000, v95
	v_add_f32_e32 v157, v168, v166
	v_fmamk_f32 v166, v156, 0xbc800000, v96
	v_fmamk_f32 v168, v156, 0xbc800000, v94
	v_mul_f32_e32 v169, v169, v169
	v_mul_f32_e32 v167, v167, v167
	v_fmac_f32_e32 v169, v168, v168
	v_fmac_f32_e32 v167, v166, v166
	v_add_f32_e32 v166, v169, v167
	v_fmamk_f32 v167, v156, 0xbc800000, v57
	v_fmamk_f32 v169, v156, 0xbc800000, v55
	v_add_f32_e32 v157, v157, v166
	v_fmamk_f32 v166, v156, 0xbc800000, v56
	v_fmamk_f32 v168, v156, 0xbc800000, v54
	v_mul_f32_e32 v169, v169, v169
	v_mul_f32_e32 v167, v167, v167
	v_fmac_f32_e32 v169, v168, v168
	v_fmac_f32_e32 v167, v166, v166
	v_add_f32_e32 v166, v169, v167
	v_fmamk_f32 v167, v156, 0xbc800000, v25
	v_fmamk_f32 v169, v156, 0xbc800000, v23
	v_add_f32_e32 v157, v166, v157
	v_fmamk_f32 v166, v156, 0xbc800000, v24
	v_fmamk_f32 v168, v156, 0xbc800000, v22
	v_mul_f32_e32 v169, v169, v169
	v_mul_f32_e32 v167, v167, v167
	v_fmac_f32_e32 v169, v168, v168
	v_fmac_f32_e32 v167, v166, v166
	v_add_f32_e32 v166, v169, v167
	v_add_f32_e32 v157, v166, v157
	v_mov_b32_e32 v166, v157
	s_nop 1
	v_permlane16_swap_b32_e32 v166, v157
	s_waitcnt lgkmcnt(0)
	v_add_f32_e32 v157, v157, v166
	v_mov_b32_e32 v166, v157
	s_nop 1
	v_permlane32_swap_b32_e32 v166, v157
	s_and_saveexec_b64 s[6:7], vcc
	s_cbranch_execz .LBB0_343
	s_lshl_b32 s8, s52, 11
	s_add_i32 s8, s2, s8
	v_mul_f32_e32 v156, 0x3c800000, v156
	v_lshl_add_u32 v167, v0, 5, s8
	s_waitcnt lgkmcnt(0)
	v_add_f32_e32 v157, v157, v166
	ds_write_b64 v167, v[156:157] offset:4096
.LBB0_343:
	s_or_b64 exec, exec, s[6:7]
	v_mov_b32_e32 v156, v123
	v_mov_b32_e32 v157, v124
	s_waitcnt lgkmcnt(0)
	v_mov_b32_e32 v166, v122
	v_mov_b32_e32 v167, v125
	v_pk_add_f32 v[156:157], v[156:157], v[166:167]
	v_mov_b32_e32 v166, v91
	v_mov_b32_e32 v167, v92
	v_mov_b32_e32 v168, v90
	v_mov_b32_e32 v169, v93
	v_pk_add_f32 v[166:167], v[166:167], v[168:169]
	v_add_f32_e32 v156, v156, v157
	v_pk_add_f32 v[166:167], v[166:167], v[166:167] op_sel:[0,1] op_sel_hi:[1,0]
	v_add_f32_e32 v156, 0, v156
	v_add_f32_e32 v168, v50, v51
	v_add_f32_e32 v170, v52, v53
	v_mov_b32_e32 v157, v18
	v_mov_b32_e32 v167, v19
	v_mov_b32_e32 v169, v20
	v_mov_b32_e32 v171, v21
	v_pk_add_f32 v[156:157], v[156:157], v[166:167]
	v_pk_add_f32 v[166:167], v[168:169], v[170:171]
	s_nop 0
	v_pk_add_f32 v[156:157], v[156:157], v[166:167]
	s_nop 0
	v_add_f32_e32 v156, v156, v157
	v_mov_b32_e32 v157, v156
	s_nop 1
	v_permlane16_swap_b32_e32 v157, v156
	s_waitcnt lgkmcnt(0)
	v_add_f32_e32 v156, v156, v157
	v_mov_b32_e32 v157, v156
	s_nop 1
	v_permlane32_swap_b32_e32 v157, v156
	s_waitcnt lgkmcnt(0)
	v_add_f32_e32 v156, v156, v157
	v_fmamk_f32 v166, v156, 0xbc800000, v125
	v_fmamk_f32 v168, v156, 0xbc800000, v123
	v_fmamk_f32 v157, v156, 0xbc800000, v124
	v_fmamk_f32 v167, v156, 0xbc800000, v122
	v_mul_f32_e32 v168, v168, v168
	v_mul_f32_e32 v166, v166, v166
	v_fmac_f32_e32 v168, v167, v167
	v_fmac_f32_e32 v166, v157, v157
	v_fmamk_f32 v167, v156, 0xbc800000, v93
	v_fmamk_f32 v169, v156, 0xbc800000, v91
	v_add_f32_e32 v157, v168, v166
	v_fmamk_f32 v166, v156, 0xbc800000, v92
	v_fmamk_f32 v168, v156, 0xbc800000, v90
	v_mul_f32_e32 v169, v169, v169
	v_mul_f32_e32 v167, v167, v167
	v_fmac_f32_e32 v169, v168, v168
	v_fmac_f32_e32 v167, v166, v166
	v_add_f32_e32 v166, v169, v167
	v_fmamk_f32 v167, v156, 0xbc800000, v53
	v_fmamk_f32 v169, v156, 0xbc800000, v51
	v_add_f32_e32 v157, v157, v166
	v_fmamk_f32 v166, v156, 0xbc800000, v52
	v_fmamk_f32 v168, v156, 0xbc800000, v50
	v_mul_f32_e32 v169, v169, v169
	v_mul_f32_e32 v167, v167, v167
	v_fmac_f32_e32 v169, v168, v168
	v_fmac_f32_e32 v167, v166, v166
	v_add_f32_e32 v166, v169, v167
	v_fmamk_f32 v167, v156, 0xbc800000, v21
	v_fmamk_f32 v169, v156, 0xbc800000, v19
	v_add_f32_e32 v157, v166, v157
	v_fmamk_f32 v166, v156, 0xbc800000, v20
	v_fmamk_f32 v168, v156, 0xbc800000, v18
	v_mul_f32_e32 v169, v169, v169
	v_mul_f32_e32 v167, v167, v167
	v_fmac_f32_e32 v169, v168, v168
	v_fmac_f32_e32 v167, v166, v166
	v_add_f32_e32 v166, v169, v167
	v_add_f32_e32 v157, v166, v157
	v_mov_b32_e32 v166, v157
	s_nop 1
	v_permlane16_swap_b32_e32 v166, v157
	s_waitcnt lgkmcnt(0)
	v_add_f32_e32 v157, v157, v166
	v_mov_b32_e32 v166, v157
	s_nop 1
	v_permlane32_swap_b32_e32 v166, v157
	s_and_saveexec_b64 s[6:7], vcc
	s_cbranch_execz .LBB0_345
	s_lshl_b32 s8, s52, 11
	s_add_i32 s8, s2, s8
	v_mul_f32_e32 v156, 0x3c800000, v156
	v_lshl_add_u32 v167, v0, 5, s8
	s_waitcnt lgkmcnt(0)
	v_add_f32_e32 v157, v157, v166
	ds_write_b64 v167, v[156:157] offset:4608
.LBB0_345:
	s_or_b64 exec, exec, s[6:7]
	v_mov_b32_e32 v156, v119
	v_mov_b32_e32 v157, v120
	s_waitcnt lgkmcnt(0)
	v_mov_b32_e32 v166, v118
	v_mov_b32_e32 v167, v121
	v_pk_add_f32 v[156:157], v[156:157], v[166:167]
	v_mov_b32_e32 v166, v79
	v_mov_b32_e32 v167, v80
	v_mov_b32_e32 v168, v78
	v_mov_b32_e32 v169, v81
	v_pk_add_f32 v[166:167], v[166:167], v[168:169]
	v_add_f32_e32 v156, v156, v157
	v_pk_add_f32 v[166:167], v[166:167], v[166:167] op_sel:[0,1] op_sel_hi:[1,0]
	v_add_f32_e32 v156, 0, v156
	v_add_f32_e32 v168, v46, v47
	v_add_f32_e32 v170, v48, v49
	v_mov_b32_e32 v157, v14
	v_mov_b32_e32 v167, v15
	v_mov_b32_e32 v169, v16
	v_mov_b32_e32 v171, v17
	v_pk_add_f32 v[156:157], v[156:157], v[166:167]
	v_pk_add_f32 v[166:167], v[168:169], v[170:171]
	s_nop 0
	v_pk_add_f32 v[156:157], v[156:157], v[166:167]
	s_nop 0
	v_add_f32_e32 v156, v156, v157
	v_mov_b32_e32 v157, v156
	s_nop 1
	v_permlane16_swap_b32_e32 v157, v156
	s_waitcnt lgkmcnt(0)
	v_add_f32_e32 v156, v156, v157
	v_mov_b32_e32 v157, v156
	s_nop 1
	v_permlane32_swap_b32_e32 v157, v156
	s_waitcnt lgkmcnt(0)
	v_add_f32_e32 v156, v156, v157
	v_fmamk_f32 v166, v156, 0xbc800000, v121
	v_fmamk_f32 v168, v156, 0xbc800000, v119
	v_fmamk_f32 v157, v156, 0xbc800000, v120
	v_fmamk_f32 v167, v156, 0xbc800000, v118
	v_mul_f32_e32 v168, v168, v168
	v_mul_f32_e32 v166, v166, v166
	v_fmac_f32_e32 v168, v167, v167
	v_fmac_f32_e32 v166, v157, v157
	v_fmamk_f32 v167, v156, 0xbc800000, v81
	v_fmamk_f32 v169, v156, 0xbc800000, v79
	v_add_f32_e32 v157, v168, v166
	v_fmamk_f32 v166, v156, 0xbc800000, v80
	v_fmamk_f32 v168, v156, 0xbc800000, v78
	v_mul_f32_e32 v169, v169, v169
	v_mul_f32_e32 v167, v167, v167
	v_fmac_f32_e32 v169, v168, v168
	v_fmac_f32_e32 v167, v166, v166
	v_add_f32_e32 v166, v169, v167
	v_fmamk_f32 v167, v156, 0xbc800000, v49
	v_fmamk_f32 v169, v156, 0xbc800000, v47
	v_add_f32_e32 v157, v157, v166
	v_fmamk_f32 v166, v156, 0xbc800000, v48
	v_fmamk_f32 v168, v156, 0xbc800000, v46
	v_mul_f32_e32 v169, v169, v169
	v_mul_f32_e32 v167, v167, v167
	v_fmac_f32_e32 v169, v168, v168
	v_fmac_f32_e32 v167, v166, v166
	v_add_f32_e32 v166, v169, v167
	v_fmamk_f32 v167, v156, 0xbc800000, v17
	v_fmamk_f32 v169, v156, 0xbc800000, v15
	v_add_f32_e32 v157, v166, v157
	v_fmamk_f32 v166, v156, 0xbc800000, v16
	v_fmamk_f32 v168, v156, 0xbc800000, v14
	v_mul_f32_e32 v169, v169, v169
	v_mul_f32_e32 v167, v167, v167
	v_fmac_f32_e32 v169, v168, v168
	v_fmac_f32_e32 v167, v166, v166
	v_add_f32_e32 v166, v169, v167
	v_add_f32_e32 v157, v166, v157
	v_mov_b32_e32 v166, v157
	s_nop 1
	v_permlane16_swap_b32_e32 v166, v157
	s_waitcnt lgkmcnt(0)
	v_add_f32_e32 v157, v157, v166
	v_mov_b32_e32 v166, v157
	s_nop 1
	v_permlane32_swap_b32_e32 v166, v157
	s_and_saveexec_b64 s[6:7], vcc
	s_cbranch_execz .LBB0_347
	s_lshl_b32 s8, s52, 11
	s_add_i32 s8, s2, s8
	v_mul_f32_e32 v156, 0x3c800000, v156
	v_lshl_add_u32 v167, v0, 5, s8
	s_waitcnt lgkmcnt(0)
	v_add_f32_e32 v157, v157, v166
	ds_write_b64 v167, v[156:157] offset:5120
.LBB0_347:
	s_or_b64 exec, exec, s[6:7]
	v_mov_b32_e32 v156, v115
	v_mov_b32_e32 v157, v116
	s_waitcnt lgkmcnt(0)
	v_mov_b32_e32 v166, v114
	v_mov_b32_e32 v167, v117
	v_pk_add_f32 v[156:157], v[156:157], v[166:167]
	v_mov_b32_e32 v166, v75
	v_mov_b32_e32 v167, v76
	v_mov_b32_e32 v168, v74
	v_mov_b32_e32 v169, v77
	v_pk_add_f32 v[166:167], v[166:167], v[168:169]
	v_add_f32_e32 v156, v156, v157
	v_pk_add_f32 v[166:167], v[166:167], v[166:167] op_sel:[0,1] op_sel_hi:[1,0]
	v_add_f32_e32 v156, 0, v156
	v_add_f32_e32 v168, v42, v43
	v_add_f32_e32 v170, v44, v45
	v_mov_b32_e32 v157, v2
	v_mov_b32_e32 v167, v3
	v_mov_b32_e32 v169, v4
	v_mov_b32_e32 v171, v5
	v_pk_add_f32 v[156:157], v[156:157], v[166:167]
	v_pk_add_f32 v[166:167], v[168:169], v[170:171]
	s_nop 0
	v_pk_add_f32 v[156:157], v[156:157], v[166:167]
	s_nop 0
	v_add_f32_e32 v156, v156, v157
	v_mov_b32_e32 v157, v156
	s_nop 1
	v_permlane16_swap_b32_e32 v157, v156
	s_waitcnt lgkmcnt(0)
	v_add_f32_e32 v156, v156, v157
	v_mov_b32_e32 v157, v156
	s_nop 1
	v_permlane32_swap_b32_e32 v157, v156
	s_waitcnt lgkmcnt(0)
	v_add_f32_e32 v156, v156, v157
	v_fmamk_f32 v166, v156, 0xbc800000, v117
	v_fmamk_f32 v168, v156, 0xbc800000, v115
	v_fmamk_f32 v157, v156, 0xbc800000, v116
	v_fmamk_f32 v167, v156, 0xbc800000, v114
	v_mul_f32_e32 v168, v168, v168
	v_mul_f32_e32 v166, v166, v166
	v_fmac_f32_e32 v168, v167, v167
	v_fmac_f32_e32 v166, v157, v157
	v_fmamk_f32 v167, v156, 0xbc800000, v77
	v_fmamk_f32 v169, v156, 0xbc800000, v75
	v_add_f32_e32 v157, v168, v166
	v_fmamk_f32 v166, v156, 0xbc800000, v76
	v_fmamk_f32 v168, v156, 0xbc800000, v74
	v_mul_f32_e32 v169, v169, v169
	v_mul_f32_e32 v167, v167, v167
	v_fmac_f32_e32 v169, v168, v168
	v_fmac_f32_e32 v167, v166, v166
	v_add_f32_e32 v166, v169, v167
	v_fmamk_f32 v167, v156, 0xbc800000, v45
	v_fmamk_f32 v169, v156, 0xbc800000, v43
	v_add_f32_e32 v157, v157, v166
	v_fmamk_f32 v166, v156, 0xbc800000, v44
	v_fmamk_f32 v168, v156, 0xbc800000, v42
	v_mul_f32_e32 v169, v169, v169
	v_mul_f32_e32 v167, v167, v167
	v_fmac_f32_e32 v169, v168, v168
	v_fmac_f32_e32 v167, v166, v166
	v_add_f32_e32 v166, v169, v167
	v_fmamk_f32 v167, v156, 0xbc800000, v5
	v_fmamk_f32 v169, v156, 0xbc800000, v3
	v_add_f32_e32 v157, v166, v157
	v_fmamk_f32 v166, v156, 0xbc800000, v4
	v_fmamk_f32 v168, v156, 0xbc800000, v2
	v_mul_f32_e32 v169, v169, v169
	v_mul_f32_e32 v167, v167, v167
	v_fmac_f32_e32 v169, v168, v168
	v_fmac_f32_e32 v167, v166, v166
	v_add_f32_e32 v166, v169, v167
	v_add_f32_e32 v157, v166, v157
	v_mov_b32_e32 v154, v157
	s_nop 1
	v_permlane16_swap_b32_e32 v154, v157
	s_waitcnt lgkmcnt(0)
	v_add_f32_e32 v154, v157, v154
	v_mov_b32_e32 v155, v154
	s_nop 1
	v_permlane32_swap_b32_e32 v155, v154
	s_and_saveexec_b64 s[6:7], vcc
	s_cbranch_execz .LBB0_349
	s_lshl_b32 s8, s52, 11
	s_add_i32 s2, s2, s8
	v_mul_f32_e32 v156, 0x3c800000, v156
	v_lshl_add_u32 v166, v0, 5, s2
	s_waitcnt lgkmcnt(0)
	v_add_f32_e32 v157, v154, v155
	ds_write_b64 v166, v[156:157] offset:5632

.LBB0_1173:
	v_readlane_b32 s6, v253, 9
	v_readlane_b32 s7, v253, 10
	s_lshl_b64 s[6:7], s[6:7], 2
	s_add_u32 s2, s12, s6
	s_addc_u32 s6, s13, s7
	s_add_u32 s30, s2, 0x100000
	s_addc_u32 s31, s6, 0
	s_lshl_b64 s[6:7], s[66:67], 2
	s_add_u32 s22, s8, s6
	s_addc_u32 s23, s9, s7
	s_add_u32 s6, s10, s6
	s_addc_u32 s7, s11, s7
	s_waitcnt vmcnt(0)
	s_barrier
	v_mbcnt_lo_u32_b32 v0, -1, 0
	v_mbcnt_hi_u32_b32 v0, -1, v0
	s_lshl_b32 s8, s16, 8
	v_ashrrev_i32_e32 v130, 2, v0
	s_or_b32 s8, s8, s43
	v_and_b32_e32 v130, -4, v130
	v_add_u32_e32 v196, s8, v130
	s_lshl_b32 s8, s14, 8
	s_ashr_i32 s9, s8, 31
	s_ashr_i32 s2, s14, 3
	s_lshl_b64 s[18:19], s[8:9], 11
	s_add_u32 s20, s12, s18
	v_and_or_b32 v212, v0, 15, s87
	s_addc_u32 s21, s13, s19
	v_ashrrev_i32_e32 v197, 31, v196
	v_add_u32_e32 v204, 0x80, v212
	v_lshl_add_u64 v[130:131], v[196:197], 1, s[20:21]
	s_mov_b64 s[20:21], 0x5200000
	v_ashrrev_i32_e32 v205, 31, v204
	v_ashrrev_i32_e32 v213, 31, v212
	v_add_u32_e32 v202, 0x90, v212
	s_mul_hi_i32 s11, s2, 0x2400
	s_mul_i32 s10, s2, 0x2400
	v_lshl_add_u64 v[130:131], v[130:131], 0, s[20:21]
	v_lshlrev_b64 v[132:133], 11, v[204:205]
	v_lshlrev_b64 v[134:135], 11, v[212:213]
	v_or_b32_e32 v210, 16, v212
	v_ashrrev_i32_e32 v203, 31, v202
	v_add_u32_e32 v200, 0xa0, v212
	v_lshl_add_u64 v[194:195], v[130:131], 0, v[134:135]
	v_ashrrev_i32_e32 v211, 31, v210
	v_or_b32_e32 v208, 32, v212
	v_or_b32_e32 v206, 48, v212
	v_lshl_add_u64 v[186:187], v[130:131], 0, v[132:133]
	v_lshlrev_b64 v[132:133], 11, v[202:203]
	v_ashrrev_i32_e32 v201, 31, v200
	v_add_u32_e32 v198, 0xb0, v212
	s_lshl_b64 s[20:21], s[10:11], 2
	global_load_dwordx2 v[146:147], v[194:195], off
	v_lshlrev_b64 v[134:135], 11, v[210:211]
	v_ashrrev_i32_e32 v209, 31, v208
	v_ashrrev_i32_e32 v207, 31, v206
	v_lshl_add_u64 v[184:185], v[130:131], 0, v[132:133]
	v_lshlrev_b64 v[132:133], 11, v[200:201]
	v_ashrrev_i32_e32 v199, 31, v198
	s_add_u32 s10, s30, s20
	v_lshl_add_u64 v[192:193], v[130:131], 0, v[134:135]
	v_lshlrev_b64 v[134:135], 11, v[208:209]
	v_lshlrev_b64 v[138:139], 11, v[206:207]
	v_lshl_add_u64 v[182:183], v[130:131], 0, v[132:133]
	v_lshlrev_b64 v[132:133], 11, v[198:199]
	s_addc_u32 s11, s31, s21
	v_lshlrev_b64 v[158:159], 2, v[196:197]
	v_lshl_add_u64 v[190:191], v[130:131], 0, v[134:135]
	v_lshl_add_u64 v[188:189], v[130:131], 0, v[138:139]
	v_lshl_add_u64 v[180:181], v[130:131], 0, v[132:133]
	v_lshl_add_u64 v[130:131], s[10:11], 0, v[158:159]
	s_mov_b64 s[10:11], 0x5000
	s_movk_i32 s2, 0x5000
	v_lshl_add_u64 v[214:215], v[130:131], 0, s[10:11]
	v_add_co_u32_e32 v130, vcc, s2, v130
	global_load_dwordx2 v[136:137], v[192:193], off
	global_load_dwordx2 v[134:135], v[190:191], off
	v_addc_co_u32_e32 v131, vcc, 0, v131, vcc
	global_load_dwordx2 v[242:243], v[188:189], off
	global_load_dwordx2 v[240:241], v[186:187], off
	global_load_dwordx2 v[238:239], v[184:185], off
	global_load_dwordx2 v[236:237], v[182:183], off
	global_load_dwordx2 v[234:235], v[180:181], off
	global_load_dwordx2 v[232:233], v[194:195], off offset:32
	global_load_dwordx2 v[230:231], v[192:193], off offset:32
	global_load_dwordx2 v[228:229], v[190:191], off offset:32
	global_load_dwordx2 v[226:227], v[188:189], off offset:32
	global_load_dwordx2 v[224:225], v[186:187], off offset:32
	global_load_dwordx2 v[222:223], v[184:185], off offset:32
	global_load_dwordx2 v[220:221], v[182:183], off offset:32
	global_load_dwordx2 v[218:219], v[180:181], off offset:32
	global_load_dwordx2 v[216:217], v[194:195], off offset:256
	global_load_dwordx2 v[176:177], v[192:193], off offset:256
	global_load_dwordx2 v[174:175], v[190:191], off offset:256
	global_load_dwordx2 v[172:173], v[188:189], off offset:256
	global_load_dwordx2 v[170:171], v[186:187], off offset:256
	global_load_dwordx2 v[168:169], v[184:185], off offset:256
	global_load_dwordx2 v[166:167], v[182:183], off offset:256
	global_load_dwordx2 v[164:165], v[180:181], off offset:256
	global_load_dwordx2 v[162:163], v[194:195], off offset:288
	global_load_dwordx2 v[160:161], v[192:193], off offset:288
	global_load_dwordx2 v[156:157], v[190:191], off offset:288
	global_load_dwordx2 v[154:155], v[188:189], off offset:288
	global_load_dwordx2 v[144:145], v[186:187], off offset:288
	global_load_dwordx2 v[142:143], v[184:185], off offset:288
	global_load_dwordx2 v[140:141], v[182:183], off offset:288
	global_load_dwordx2 v[138:139], v[180:181], off offset:288
	s_lshl_b32 s2, s92, 3
	global_load_dwordx4 v[130:133], v[130:131], off
	s_add_i32 s2, s2, 0
	s_waitcnt vmcnt(0)
	v_cvt_f32_f16_e32 v148, v147
	v_cvt_f32_f16_sdwa v149, v147 dst_sel:DWORD dst_unused:UNUSED_PAD src0_sel:WORD_1
	v_cvt_f32_f16_e32 v150, v146
	v_cvt_f32_f16_sdwa v151, v146 dst_sel:DWORD dst_unused:UNUSED_PAD src0_sel:WORD_1
	v_pk_mul_f32 v[148:149], v[148:149], s[90:91] op_sel_hi:[1,0]
	v_pk_mul_f32 v[146:147], v[150:151], s[90:91] op_sel_hi:[1,0]
	v_pk_fma_f32 v[152:153], v[124:125], v[132:133], v[148:149]
	v_pk_fma_f32 v[150:151], v[122:123], v[130:131], v[146:147]
	v_cvt_f32_f16_e32 v122, v137
	v_cvt_f32_f16_sdwa v123, v137 dst_sel:DWORD dst_unused:UNUSED_PAD src0_sel:WORD_1
	v_cvt_f32_f16_e32 v124, v136
	v_cvt_f32_f16_sdwa v125, v136 dst_sel:DWORD dst_unused:UNUSED_PAD src0_sel:WORD_1
	v_pk_mul_f32 v[122:123], v[122:123], s[90:91] op_sel_hi:[1,0]
	v_pk_mul_f32 v[124:125], v[124:125], s[90:91] op_sel_hi:[1,0]
	v_pk_fma_f32 v[148:149], v[120:121], v[132:133], v[122:123]
	v_pk_fma_f32 v[146:147], v[118:119], v[130:131], v[124:125]
	v_cvt_f32_f16_e32 v118, v135
	v_cvt_f32_f16_sdwa v119, v135 dst_sel:DWORD dst_unused:UNUSED_PAD src0_sel:WORD_1
	v_cvt_f32_f16_e32 v120, v134
	v_cvt_f32_f16_sdwa v121, v134 dst_sel:DWORD dst_unused:UNUSED_PAD src0_sel:WORD_1
	v_pk_mul_f32 v[118:119], v[118:119], s[90:91] op_sel_hi:[1,0]
	v_pk_mul_f32 v[120:121], v[120:121], s[90:91] op_sel_hi:[1,0]
	v_pk_fma_f32 v[136:137], v[116:117], v[132:133], v[118:119]
	v_pk_fma_f32 v[134:135], v[114:115], v[130:131], v[120:121]
	v_cvt_f32_f16_e32 v114, v243
	v_cvt_f32_f16_sdwa v115, v243 dst_sel:DWORD dst_unused:UNUSED_PAD src0_sel:WORD_1
	v_cvt_f32_f16_e32 v116, v242
	v_cvt_f32_f16_sdwa v117, v242 dst_sel:DWORD dst_unused:UNUSED_PAD src0_sel:WORD_1
	v_pk_mul_f32 v[114:115], v[114:115], s[90:91] op_sel_hi:[1,0]
	v_pk_mul_f32 v[116:117], v[116:117], s[90:91] op_sel_hi:[1,0]
	v_pk_fma_f32 v[120:121], v[112:113], v[132:133], v[114:115]
	v_pk_fma_f32 v[118:119], v[110:111], v[130:131], v[116:117]
	v_cvt_f32_f16_e32 v110, v241
	v_cvt_f32_f16_sdwa v111, v241 dst_sel:DWORD dst_unused:UNUSED_PAD src0_sel:WORD_1
	v_cvt_f32_f16_e32 v112, v240
	v_cvt_f32_f16_sdwa v113, v240 dst_sel:DWORD dst_unused:UNUSED_PAD src0_sel:WORD_1
	v_pk_mul_f32 v[110:111], v[110:111], s[90:91] op_sel_hi:[1,0]
	v_pk_mul_f32 v[112:113], v[112:113], s[90:91] op_sel_hi:[1,0]
	v_pk_fma_f32 v[124:125], v[108:109], v[132:133], v[110:111]
	v_pk_fma_f32 v[122:123], v[106:107], v[130:131], v[112:113]
	v_cvt_f32_f16_e32 v106, v239
	v_cvt_f32_f16_sdwa v107, v239 dst_sel:DWORD dst_unused:UNUSED_PAD src0_sel:WORD_1
	v_cvt_f32_f16_e32 v108, v238
	v_cvt_f32_f16_sdwa v109, v238 dst_sel:DWORD dst_unused:UNUSED_PAD src0_sel:WORD_1
	v_pk_mul_f32 v[106:107], v[106:107], s[90:91] op_sel_hi:[1,0]
	v_pk_mul_f32 v[108:109], v[108:109], s[90:91] op_sel_hi:[1,0]
	v_pk_fma_f32 v[116:117], v[100:101], v[132:133], v[106:107]
	v_pk_fma_f32 v[114:115], v[98:99], v[130:131], v[108:109]
	v_cvt_f32_f16_e32 v98, v237
	v_cvt_f32_f16_sdwa v99, v237 dst_sel:DWORD dst_unused:UNUSED_PAD src0_sel:WORD_1
	v_cvt_f32_f16_e32 v100, v236
	v_cvt_f32_f16_sdwa v101, v236 dst_sel:DWORD dst_unused:UNUSED_PAD src0_sel:WORD_1
	v_pk_mul_f32 v[98:99], v[98:99], s[90:91] op_sel_hi:[1,0]
	v_pk_mul_f32 v[100:101], v[100:101], s[90:91] op_sel_hi:[1,0]
	v_pk_fma_f32 v[112:113], v[88:89], v[132:133], v[98:99]
	v_pk_fma_f32 v[110:111], v[86:87], v[130:131], v[100:101]
	v_cvt_f32_f16_e32 v86, v235
	v_cvt_f32_f16_sdwa v87, v235 dst_sel:DWORD dst_unused:UNUSED_PAD src0_sel:WORD_1
	v_cvt_f32_f16_e32 v88, v234
	v_cvt_f32_f16_sdwa v89, v234 dst_sel:DWORD dst_unused:UNUSED_PAD src0_sel:WORD_1
	v_pk_mul_f32 v[86:87], v[86:87], s[90:91] op_sel_hi:[1,0]
	v_pk_mul_f32 v[88:89], v[88:89], s[90:91] op_sel_hi:[1,0]
	v_pk_fma_f32 v[108:109], v[80:81], v[132:133], v[86:87]
	v_pk_fma_f32 v[106:107], v[78:79], v[130:131], v[88:89]
	v_cvt_f32_f16_e32 v78, v233
	global_load_dwordx4 v[130:133], v[214:215], off offset:64
	v_cvt_f32_f16_sdwa v79, v233 dst_sel:DWORD dst_unused:UNUSED_PAD src0_sel:WORD_1
	v_cvt_f32_f16_e32 v80, v232
	v_cvt_f32_f16_sdwa v81, v232 dst_sel:DWORD dst_unused:UNUSED_PAD src0_sel:WORD_1
	s_waitcnt vmcnt(0)
	v_pk_mul_f32 v[86:87], v[104:105], v[132:133]
	v_pk_mul_f32 v[88:89], v[102:103], v[130:131]
	v_pk_fma_f32 v[104:105], v[78:79], s[90:91], v[86:87] op_sel_hi:[1,0,1]
	v_pk_fma_f32 v[102:103], v[80:81], s[90:91], v[88:89] op_sel_hi:[1,0,1]
	v_cvt_f32_f16_e32 v78, v231
	v_cvt_f32_f16_sdwa v79, v231 dst_sel:DWORD dst_unused:UNUSED_PAD src0_sel:WORD_1
	v_cvt_f32_f16_e32 v80, v230
	v_cvt_f32_f16_sdwa v81, v230 dst_sel:DWORD dst_unused:UNUSED_PAD src0_sel:WORD_1
	v_pk_mul_f32 v[86:87], v[96:97], v[132:133]
	v_pk_mul_f32 v[88:89], v[94:95], v[130:131]
	v_pk_fma_f32 v[100:101], v[78:79], s[90:91], v[86:87] op_sel_hi:[1,0,1]
	v_pk_fma_f32 v[98:99], v[80:81], s[90:91], v[88:89] op_sel_hi:[1,0,1]
	v_cvt_f32_f16_e32 v78, v229
	v_cvt_f32_f16_sdwa v79, v229 dst_sel:DWORD dst_unused:UNUSED_PAD src0_sel:WORD_1
	v_cvt_f32_f16_e32 v80, v228
	v_cvt_f32_f16_sdwa v81, v228 dst_sel:DWORD dst_unused:UNUSED_PAD src0_sel:WORD_1
	v_pk_mul_f32 v[86:87], v[92:93], v[132:133]
	v_pk_mul_f32 v[88:89], v[90:91], v[130:131]
	v_pk_fma_f32 v[96:97], v[78:79], s[90:91], v[86:87] op_sel_hi:[1,0,1]
	v_pk_fma_f32 v[94:95], v[80:81], s[90:91], v[88:89] op_sel_hi:[1,0,1]
	v_cvt_f32_f16_e32 v78, v227
	v_cvt_f32_f16_sdwa v79, v227 dst_sel:DWORD dst_unused:UNUSED_PAD src0_sel:WORD_1
	v_cvt_f32_f16_e32 v80, v226
	v_cvt_f32_f16_sdwa v81, v226 dst_sel:DWORD dst_unused:UNUSED_PAD src0_sel:WORD_1
	v_pk_mul_f32 v[84:85], v[84:85], v[132:133]
	v_pk_mul_f32 v[82:83], v[82:83], v[130:131]
	v_pk_fma_f32 v[92:93], v[78:79], s[90:91], v[84:85] op_sel_hi:[1,0,1]
	v_pk_fma_f32 v[90:91], v[80:81], s[90:91], v[82:83] op_sel_hi:[1,0,1]
	v_cvt_f32_f16_e32 v78, v225
	v_cvt_f32_f16_sdwa v79, v225 dst_sel:DWORD dst_unused:UNUSED_PAD src0_sel:WORD_1
	v_cvt_f32_f16_e32 v80, v224
	v_cvt_f32_f16_sdwa v81, v224 dst_sel:DWORD dst_unused:UNUSED_PAD src0_sel:WORD_1
	v_pk_mul_f32 v[76:77], v[76:77], v[132:133]
	v_pk_mul_f32 v[74:75], v[74:75], v[130:131]
	v_pk_fma_f32 v[88:89], v[78:79], s[90:91], v[76:77] op_sel_hi:[1,0,1]
	v_pk_fma_f32 v[86:87], v[80:81], s[90:91], v[74:75] op_sel_hi:[1,0,1]
	v_cvt_f32_f16_e32 v74, v223
	v_cvt_f32_f16_sdwa v75, v223 dst_sel:DWORD dst_unused:UNUSED_PAD src0_sel:WORD_1
	v_cvt_f32_f16_e32 v76, v222
	v_cvt_f32_f16_sdwa v77, v222 dst_sel:DWORD dst_unused:UNUSED_PAD src0_sel:WORD_1
	v_pk_mul_f32 v[64:65], v[64:65], v[132:133]
	v_pk_mul_f32 v[62:63], v[62:63], v[130:131]
	v_pk_fma_f32 v[84:85], v[74:75], s[90:91], v[64:65] op_sel_hi:[1,0,1]
	v_pk_fma_f32 v[82:83], v[76:77], s[90:91], v[62:63] op_sel_hi:[1,0,1]
	v_cvt_f32_f16_e32 v62, v221
	v_cvt_f32_f16_sdwa v63, v221 dst_sel:DWORD dst_unused:UNUSED_PAD src0_sel:WORD_1
	v_cvt_f32_f16_e32 v64, v220
	v_cvt_f32_f16_sdwa v65, v220 dst_sel:DWORD dst_unused:UNUSED_PAD src0_sel:WORD_1
	v_pk_mul_f32 v[60:61], v[60:61], v[132:133]
	v_pk_mul_f32 v[58:59], v[58:59], v[130:131]
	v_pk_fma_f32 v[80:81], v[62:63], s[90:91], v[60:61] op_sel_hi:[1,0,1]
	v_pk_fma_f32 v[78:79], v[64:65], s[90:91], v[58:59] op_sel_hi:[1,0,1]
	v_cvt_f32_f16_e32 v58, v219
	v_cvt_f32_f16_sdwa v59, v219 dst_sel:DWORD dst_unused:UNUSED_PAD src0_sel:WORD_1
	v_cvt_f32_f16_e32 v60, v218
	v_cvt_f32_f16_sdwa v61, v218 dst_sel:DWORD dst_unused:UNUSED_PAD src0_sel:WORD_1
	v_pk_mul_f32 v[56:57], v[56:57], v[132:133]
	v_pk_mul_f32 v[54:55], v[54:55], v[130:131]
	v_pk_fma_f32 v[76:77], v[58:59], s[90:91], v[56:57] op_sel_hi:[1,0,1]
	v_pk_fma_f32 v[74:75], v[60:61], s[90:91], v[54:55] op_sel_hi:[1,0,1]
	s_nop 0
	global_load_dwordx4 v[130:133], v[214:215], off offset:512
	v_cvt_f32_f16_e32 v54, v217
	v_cvt_f32_f16_sdwa v55, v217 dst_sel:DWORD dst_unused:UNUSED_PAD src0_sel:WORD_1
	v_cvt_f32_f16_e32 v56, v216
	v_cvt_f32_f16_sdwa v57, v216 dst_sel:DWORD dst_unused:UNUSED_PAD src0_sel:WORD_1
	s_waitcnt vmcnt(0)
	v_pk_mul_f32 v[58:59], v[72:73], v[132:133]
	v_pk_mul_f32 v[60:61], v[70:71], v[130:131]
	v_pk_fma_f32 v[64:65], v[54:55], s[90:91], v[58:59] op_sel_hi:[1,0,1]
	v_pk_fma_f32 v[62:63], v[56:57], s[90:91], v[60:61] op_sel_hi:[1,0,1]
	v_cvt_f32_f16_e32 v54, v177
	v_cvt_f32_f16_sdwa v55, v177 dst_sel:DWORD dst_unused:UNUSED_PAD src0_sel:WORD_1
	v_cvt_f32_f16_e32 v56, v176
	v_cvt_f32_f16_sdwa v57, v176 dst_sel:DWORD dst_unused:UNUSED_PAD src0_sel:WORD_1
	v_pk_mul_f32 v[58:59], v[68:69], v[132:133]
	v_pk_mul_f32 v[60:61], v[66:67], v[130:131]
	v_pk_fma_f32 v[72:73], v[54:55], s[90:91], v[58:59] op_sel_hi:[1,0,1]
	v_pk_fma_f32 v[70:71], v[56:57], s[90:91], v[60:61] op_sel_hi:[1,0,1]
	v_cvt_f32_f16_e32 v54, v175
	v_cvt_f32_f16_sdwa v55, v175 dst_sel:DWORD dst_unused:UNUSED_PAD src0_sel:WORD_1
	v_cvt_f32_f16_e32 v56, v174
	v_cvt_f32_f16_sdwa v57, v174 dst_sel:DWORD dst_unused:UNUSED_PAD src0_sel:WORD_1
	v_pk_mul_f32 v[52:53], v[52:53], v[132:133]
	v_pk_mul_f32 v[50:51], v[50:51], v[130:131]
	v_pk_fma_f32 v[68:69], v[54:55], s[90:91], v[52:53] op_sel_hi:[1,0,1]
	v_pk_fma_f32 v[66:67], v[56:57], s[90:91], v[50:51] op_sel_hi:[1,0,1]
	v_cvt_f32_f16_e32 v50, v173
	v_cvt_f32_f16_sdwa v51, v173 dst_sel:DWORD dst_unused:UNUSED_PAD src0_sel:WORD_1
	v_cvt_f32_f16_e32 v52, v172
	v_cvt_f32_f16_sdwa v53, v172 dst_sel:DWORD dst_unused:UNUSED_PAD src0_sel:WORD_1
	v_pk_mul_f32 v[48:49], v[48:49], v[132:133]
	v_pk_mul_f32 v[46:47], v[46:47], v[130:131]
	v_pk_fma_f32 v[60:61], v[50:51], s[90:91], v[48:49] op_sel_hi:[1,0,1]
	v_pk_fma_f32 v[58:59], v[52:53], s[90:91], v[46:47] op_sel_hi:[1,0,1]
	v_cvt_f32_f16_e32 v46, v171
	v_cvt_f32_f16_sdwa v47, v171 dst_sel:DWORD dst_unused:UNUSED_PAD src0_sel:WORD_1
	v_cvt_f32_f16_e32 v48, v170
	v_cvt_f32_f16_sdwa v49, v170 dst_sel:DWORD dst_unused:UNUSED_PAD src0_sel:WORD_1
	v_pk_mul_f32 v[40:41], v[40:41], v[132:133]
	v_pk_mul_f32 v[38:39], v[38:39], v[130:131]
	v_pk_fma_f32 v[56:57], v[46:47], s[90:91], v[40:41] op_sel_hi:[1,0,1]
	v_pk_fma_f32 v[54:55], v[48:49], s[90:91], v[38:39] op_sel_hi:[1,0,1]
	v_cvt_f32_f16_e32 v38, v169
	v_cvt_f32_f16_sdwa v39, v169 dst_sel:DWORD dst_unused:UNUSED_PAD src0_sel:WORD_1
	v_cvt_f32_f16_e32 v40, v168
	v_cvt_f32_f16_sdwa v41, v168 dst_sel:DWORD dst_unused:UNUSED_PAD src0_sel:WORD_1
	v_pk_mul_f32 v[36:37], v[36:37], v[132:133]
	v_pk_mul_f32 v[34:35], v[34:35], v[130:131]
	v_pk_fma_f32 v[52:53], v[38:39], s[90:91], v[36:37] op_sel_hi:[1,0,1]
	v_pk_fma_f32 v[50:51], v[40:41], s[90:91], v[34:35] op_sel_hi:[1,0,1]
	v_cvt_f32_f16_e32 v34, v167
	v_cvt_f32_f16_sdwa v35, v167 dst_sel:DWORD dst_unused:UNUSED_PAD src0_sel:WORD_1
	v_cvt_f32_f16_e32 v36, v166
	v_cvt_f32_f16_sdwa v37, v166 dst_sel:DWORD dst_unused:UNUSED_PAD src0_sel:WORD_1
	v_pk_mul_f32 v[20:21], v[20:21], v[132:133]
	v_pk_mul_f32 v[18:19], v[18:19], v[130:131]
	v_pk_fma_f32 v[48:49], v[34:35], s[90:91], v[20:21] op_sel_hi:[1,0,1]
	v_pk_fma_f32 v[46:47], v[36:37], s[90:91], v[18:19] op_sel_hi:[1,0,1]
	v_cvt_f32_f16_e32 v18, v165
	v_cvt_f32_f16_sdwa v19, v165 dst_sel:DWORD dst_unused:UNUSED_PAD src0_sel:WORD_1
	v_cvt_f32_f16_e32 v20, v164
	v_cvt_f32_f16_sdwa v21, v164 dst_sel:DWORD dst_unused:UNUSED_PAD src0_sel:WORD_1
	v_pk_mul_f32 v[12:13], v[12:13], v[132:133]
	v_pk_mul_f32 v[10:11], v[10:11], v[130:131]
	v_pk_fma_f32 v[40:41], v[18:19], s[90:91], v[12:13] op_sel_hi:[1,0,1]
	v_pk_fma_f32 v[38:39], v[20:21], s[90:91], v[10:11] op_sel_hi:[1,0,1]
	s_nop 0
	global_load_dwordx4 v[130:133], v[214:215], off offset:576
	v_cvt_f32_f16_e32 v10, v163
	v_cvt_f32_f16_sdwa v11, v163 dst_sel:DWORD dst_unused:UNUSED_PAD src0_sel:WORD_1
	v_cvt_f32_f16_e32 v12, v162
	v_cvt_f32_f16_sdwa v13, v162 dst_sel:DWORD dst_unused:UNUSED_PAD src0_sel:WORD_1
	v_and_b32_e32 v163, 64, v249
	v_xor_b32_e32 v162, 16, v249
	v_add_u32_e32 v163, 64, v163
	v_cmp_lt_i32_e32 vcc, v162, v163
	v_xor_b32_e32 v164, 32, v249
	v_mov_b32_e32 v165, v152
	v_cndmask_b32_e32 v162, v249, v162, vcc
	v_cmp_lt_i32_e32 vcc, v164, v163
	v_mov_b32_e32 v166, v150
	v_mov_b32_e32 v167, v153
	v_cndmask_b32_e32 v163, v249, v164, vcc
	v_mov_b32_e32 v164, v151
	v_pk_add_f32 v[164:165], v[164:165], v[166:167]
	v_mov_b32_e32 v166, v103
	v_mov_b32_e32 v167, v104
	v_mov_b32_e32 v168, v102
	v_mov_b32_e32 v169, v105
	v_pk_add_f32 v[166:167], v[166:167], v[168:169]
	v_add_f32_e32 v164, v164, v165
	v_pk_add_f32 v[166:167], v[166:167], v[166:167] op_sel:[0,1] op_sel_hi:[1,0]
	v_add_f32_e32 v164, 0, v164
	v_add_f32_e32 v168, v62, v63
	v_add_f32_e32 v170, v64, v65
	v_lshlrev_b32_e32 v162, 2, v162
	v_lshlrev_b32_e32 v163, 2, v163
	v_cmp_gt_u32_e32 vcc, 16, v0
	s_waitcnt vmcnt(0)
	v_pk_mul_f32 v[20:21], v[128:129], v[132:133]
	v_pk_mul_f32 v[18:19], v[126:127], v[130:131]
	v_pk_fma_f32 v[20:21], v[10:11], s[90:91], v[20:21] op_sel_hi:[1,0,1]
	v_pk_fma_f32 v[18:19], v[12:13], s[90:91], v[18:19] op_sel_hi:[1,0,1]
	v_cvt_f32_f16_e32 v12, v161
	v_cvt_f32_f16_sdwa v13, v161 dst_sel:DWORD dst_unused:UNUSED_PAD src0_sel:WORD_1
	v_cvt_f32_f16_e32 v10, v160
	v_cvt_f32_f16_sdwa v11, v160 dst_sel:DWORD dst_unused:UNUSED_PAD src0_sel:WORD_1
	v_pk_mul_f32 v[34:35], v[44:45], v[132:133]
	v_pk_mul_f32 v[36:37], v[42:43], v[130:131]
	v_pk_fma_f32 v[12:13], v[12:13], s[90:91], v[34:35] op_sel_hi:[1,0,1]
	v_pk_fma_f32 v[10:11], v[10:11], s[90:91], v[36:37] op_sel_hi:[1,0,1]
	v_cvt_f32_f16_e32 v34, v157
	v_cvt_f32_f16_sdwa v35, v157 dst_sel:DWORD dst_unused:UNUSED_PAD src0_sel:WORD_1
	v_cvt_f32_f16_e32 v36, v156
	v_cvt_f32_f16_sdwa v37, v156 dst_sel:DWORD dst_unused:UNUSED_PAD src0_sel:WORD_1
	v_pk_mul_f32 v[32:33], v[32:33], v[132:133]
	v_pk_mul_f32 v[30:31], v[30:31], v[130:131]
	v_pk_fma_f32 v[44:45], v[34:35], s[90:91], v[32:33] op_sel_hi:[1,0,1]
	v_pk_fma_f32 v[42:43], v[36:37], s[90:91], v[30:31] op_sel_hi:[1,0,1]
	v_cvt_f32_f16_e32 v30, v155
	v_cvt_f32_f16_sdwa v31, v155 dst_sel:DWORD dst_unused:UNUSED_PAD src0_sel:WORD_1
	v_cvt_f32_f16_e32 v32, v154
	v_cvt_f32_f16_sdwa v33, v154 dst_sel:DWORD dst_unused:UNUSED_PAD src0_sel:WORD_1
	v_pk_mul_f32 v[28:29], v[28:29], v[132:133]
	v_pk_mul_f32 v[26:27], v[26:27], v[130:131]
	v_pk_fma_f32 v[36:37], v[30:31], s[90:91], v[28:29] op_sel_hi:[1,0,1]
	v_pk_fma_f32 v[34:35], v[32:33], s[90:91], v[26:27] op_sel_hi:[1,0,1]
	v_cvt_f32_f16_e32 v26, v145
	v_cvt_f32_f16_sdwa v27, v145 dst_sel:DWORD dst_unused:UNUSED_PAD src0_sel:WORD_1
	v_cvt_f32_f16_e32 v28, v144
	v_cvt_f32_f16_sdwa v29, v144 dst_sel:DWORD dst_unused:UNUSED_PAD src0_sel:WORD_1
	v_pk_mul_f32 v[24:25], v[24:25], v[132:133]
	v_pk_mul_f32 v[22:23], v[22:23], v[130:131]
	v_pk_fma_f32 v[32:33], v[26:27], s[90:91], v[24:25] op_sel_hi:[1,0,1]
	v_pk_fma_f32 v[30:31], v[28:29], s[90:91], v[22:23] op_sel_hi:[1,0,1]
	v_cvt_f32_f16_e32 v22, v143
	v_cvt_f32_f16_sdwa v23, v143 dst_sel:DWORD dst_unused:UNUSED_PAD src0_sel:WORD_1
	v_cvt_f32_f16_e32 v24, v142
	v_cvt_f32_f16_sdwa v25, v142 dst_sel:DWORD dst_unused:UNUSED_PAD src0_sel:WORD_1
	v_pk_mul_f32 v[16:17], v[16:17], v[132:133]
	v_pk_mul_f32 v[14:15], v[14:15], v[130:131]
	v_pk_fma_f32 v[28:29], v[22:23], s[90:91], v[16:17] op_sel_hi:[1,0,1]
	v_pk_fma_f32 v[26:27], v[24:25], s[90:91], v[14:15] op_sel_hi:[1,0,1]
	v_cvt_f32_f16_e32 v14, v141
	v_cvt_f32_f16_sdwa v15, v141 dst_sel:DWORD dst_unused:UNUSED_PAD src0_sel:WORD_1
	v_cvt_f32_f16_e32 v16, v140
	v_cvt_f32_f16_sdwa v17, v140 dst_sel:DWORD dst_unused:UNUSED_PAD src0_sel:WORD_1
	v_pk_mul_f32 v[8:9], v[8:9], v[132:133]
	v_pk_mul_f32 v[6:7], v[6:7], v[130:131]
	v_pk_fma_f32 v[8:9], v[14:15], s[90:91], v[8:9] op_sel_hi:[1,0,1]
	v_pk_fma_f32 v[6:7], v[16:17], s[90:91], v[6:7] op_sel_hi:[1,0,1]
	v_cvt_f32_f16_e32 v14, v139
	v_cvt_f32_f16_sdwa v15, v139 dst_sel:DWORD dst_unused:UNUSED_PAD src0_sel:WORD_1
	v_cvt_f32_f16_e32 v16, v138
	v_cvt_f32_f16_sdwa v17, v138 dst_sel:DWORD dst_unused:UNUSED_PAD src0_sel:WORD_1
	v_pk_mul_f32 v[4:5], v[4:5], v[132:133]
	v_pk_mul_f32 v[2:3], v[2:3], v[130:131]
	v_pk_fma_f32 v[4:5], v[14:15], s[90:91], v[4:5] op_sel_hi:[1,0,1]
	v_pk_fma_f32 v[2:3], v[16:17], s[90:91], v[2:3] op_sel_hi:[1,0,1]
	s_nop 0
	v_lshl_add_u64 v[14:15], s[22:23], 0, v[158:159]
	v_lshl_add_u64 v[22:23], s[6:7], 0, v[158:159]
	global_load_dwordx4 v[154:157], v[14:15], off
	global_load_dwordx4 v[158:161], v[22:23], off
	global_load_dwordx4 v[138:141], v[14:15], off offset:64
	global_load_dwordx4 v[142:145], v[22:23], off offset:64
	global_load_dwordx4 v[126:129], v[14:15], off offset:512
	global_load_dwordx4 v[130:133], v[22:23], off offset:512
	s_nop 0
	global_load_dwordx4 v[14:17], v[14:15], off offset:576
	s_nop 0
	global_load_dwordx4 v[22:25], v[22:23], off offset:576
	v_mov_b32_e32 v165, v18
	v_mov_b32_e32 v167, v19
	v_mov_b32_e32 v169, v20
	v_mov_b32_e32 v171, v21
	v_pk_add_f32 v[164:165], v[164:165], v[166:167]
	v_pk_add_f32 v[166:167], v[168:169], v[170:171]
	s_nop 0
	v_pk_add_f32 v[164:165], v[164:165], v[166:167]
	s_nop 0
	v_add_f32_e32 v164, v164, v165
	v_mov_b32_e32 v165, v164
	s_nop 1
	v_permlane16_swap_b32_e32 v165, v164
	s_waitcnt lgkmcnt(0)
	v_add_f32_e32 v164, v164, v165
	v_mov_b32_e32 v165, v164
	s_nop 1
	v_permlane32_swap_b32_e32 v165, v164
	s_waitcnt lgkmcnt(0)
	v_add_f32_e32 v164, v164, v165
	v_fmamk_f32 v166, v164, 0xbc800000, v153
	v_fmamk_f32 v168, v164, 0xbc800000, v151
	v_fmamk_f32 v165, v164, 0xbc800000, v152
	v_fmamk_f32 v167, v164, 0xbc800000, v150
	v_mul_f32_e32 v168, v168, v168
	v_mul_f32_e32 v166, v166, v166
	v_fmac_f32_e32 v168, v167, v167
	v_fmac_f32_e32 v166, v165, v165
	v_fmamk_f32 v167, v164, 0xbc800000, v105
	v_fmamk_f32 v169, v164, 0xbc800000, v103
	v_add_f32_e32 v165, v168, v166
	v_fmamk_f32 v166, v164, 0xbc800000, v104
	v_fmamk_f32 v168, v164, 0xbc800000, v102
	v_mul_f32_e32 v169, v169, v169
	v_mul_f32_e32 v167, v167, v167
	v_fmac_f32_e32 v169, v168, v168
	v_fmac_f32_e32 v167, v166, v166
	v_add_f32_e32 v166, v169, v167
	v_fmamk_f32 v167, v164, 0xbc800000, v65
	v_fmamk_f32 v169, v164, 0xbc800000, v63
	v_add_f32_e32 v165, v165, v166
	v_fmamk_f32 v166, v164, 0xbc800000, v64
	v_fmamk_f32 v168, v164, 0xbc800000, v62
	v_mul_f32_e32 v169, v169, v169
	v_mul_f32_e32 v167, v167, v167
	v_fmac_f32_e32 v169, v168, v168
	v_fmac_f32_e32 v167, v166, v166
	v_add_f32_e32 v166, v169, v167
	v_fmamk_f32 v167, v164, 0xbc800000, v21
	v_fmamk_f32 v169, v164, 0xbc800000, v19
	v_add_f32_e32 v165, v166, v165
	v_fmamk_f32 v166, v164, 0xbc800000, v20
	v_fmamk_f32 v168, v164, 0xbc800000, v18
	v_mul_f32_e32 v169, v169, v169
	v_mul_f32_e32 v167, v167, v167
	v_fmac_f32_e32 v169, v168, v168
	v_fmac_f32_e32 v167, v166, v166
	v_add_f32_e32 v166, v169, v167
	v_add_f32_e32 v165, v166, v165
	v_mov_b32_e32 v166, v165
	s_nop 1
	v_permlane16_swap_b32_e32 v166, v165
	s_waitcnt lgkmcnt(0)
	v_add_f32_e32 v165, v165, v166
	v_mov_b32_e32 v166, v165
	s_nop 1
	v_permlane32_swap_b32_e32 v166, v165
	s_and_saveexec_b64 s[6:7], vcc
	s_cbranch_execz .LBB0_1175
	s_lshl_b32 s9, s68, 11
	s_add_i32 s9, s2, s9
	v_mul_f32_e32 v164, 0x3c800000, v164
	v_lshl_add_u32 v167, v0, 5, s9
	s_waitcnt lgkmcnt(0)
	v_add_f32_e32 v165, v165, v166
	ds_write_b64 v167, v[164:165]
.LBB0_1175:
	s_or_b64 exec, exec, s[6:7]
	v_mov_b32_e32 v164, v147
	v_mov_b32_e32 v165, v148
	s_waitcnt lgkmcnt(0)
	v_mov_b32_e32 v166, v146
	v_mov_b32_e32 v167, v149
	v_pk_add_f32 v[164:165], v[164:165], v[166:167]
	v_mov_b32_e32 v166, v99
	v_mov_b32_e32 v167, v100
	v_mov_b32_e32 v168, v98
	v_mov_b32_e32 v169, v101
	v_pk_add_f32 v[166:167], v[166:167], v[168:169]
	v_add_f32_e32 v164, v164, v165
	v_pk_add_f32 v[166:167], v[166:167], v[166:167] op_sel:[0,1] op_sel_hi:[1,0]
	v_add_f32_e32 v164, 0, v164
	v_add_f32_e32 v168, v70, v71
	v_add_f32_e32 v170, v72, v73
	v_mov_b32_e32 v165, v10
	v_mov_b32_e32 v167, v11
	v_mov_b32_e32 v169, v12
	v_mov_b32_e32 v171, v13
	v_pk_add_f32 v[164:165], v[164:165], v[166:167]
	v_pk_add_f32 v[166:167], v[168:169], v[170:171]
	s_nop 0
	v_pk_add_f32 v[164:165], v[164:165], v[166:167]
	s_nop 0
	v_add_f32_e32 v164, v164, v165
	v_mov_b32_e32 v165, v164
	s_nop 1
	v_permlane16_swap_b32_e32 v165, v164
	s_waitcnt lgkmcnt(0)
	v_add_f32_e32 v164, v164, v165
	v_mov_b32_e32 v165, v164
	s_nop 1
	v_permlane32_swap_b32_e32 v165, v164
	s_waitcnt lgkmcnt(0)
	v_add_f32_e32 v164, v164, v165
	v_fmamk_f32 v166, v164, 0xbc800000, v149
	v_fmamk_f32 v168, v164, 0xbc800000, v147
	v_fmamk_f32 v165, v164, 0xbc800000, v148
	v_fmamk_f32 v167, v164, 0xbc800000, v146
	v_mul_f32_e32 v168, v168, v168
	v_mul_f32_e32 v166, v166, v166
	v_fmac_f32_e32 v168, v167, v167
	v_fmac_f32_e32 v166, v165, v165
	v_fmamk_f32 v167, v164, 0xbc800000, v101
	v_fmamk_f32 v169, v164, 0xbc800000, v99
	v_add_f32_e32 v165, v168, v166
	v_fmamk_f32 v166, v164, 0xbc800000, v100
	v_fmamk_f32 v168, v164, 0xbc800000, v98
	v_mul_f32_e32 v169, v169, v169
	v_mul_f32_e32 v167, v167, v167
	v_fmac_f32_e32 v169, v168, v168
	v_fmac_f32_e32 v167, v166, v166
	v_add_f32_e32 v166, v169, v167
	v_fmamk_f32 v167, v164, 0xbc800000, v73
	v_fmamk_f32 v169, v164, 0xbc800000, v71
	v_add_f32_e32 v165, v165, v166
	v_fmamk_f32 v166, v164, 0xbc800000, v72
	v_fmamk_f32 v168, v164, 0xbc800000, v70
	v_mul_f32_e32 v169, v169, v169
	v_mul_f32_e32 v167, v167, v167
	v_fmac_f32_e32 v169, v168, v168
	v_fmac_f32_e32 v167, v166, v166
	v_add_f32_e32 v166, v169, v167
	v_fmamk_f32 v167, v164, 0xbc800000, v13
	v_fmamk_f32 v169, v164, 0xbc800000, v11
	v_add_f32_e32 v165, v166, v165
	v_fmamk_f32 v166, v164, 0xbc800000, v12
	v_fmamk_f32 v168, v164, 0xbc800000, v10
	v_mul_f32_e32 v169, v169, v169
	v_mul_f32_e32 v167, v167, v167
	v_fmac_f32_e32 v169, v168, v168
	v_fmac_f32_e32 v167, v166, v166
	v_add_f32_e32 v166, v169, v167
	v_add_f32_e32 v165, v166, v165
	v_mov_b32_e32 v166, v165
	s_nop 1
	v_permlane16_swap_b32_e32 v166, v165
	s_waitcnt lgkmcnt(0)
	v_add_f32_e32 v165, v165, v166
	v_mov_b32_e32 v166, v165
	s_nop 1
	v_permlane32_swap_b32_e32 v166, v165
	s_and_saveexec_b64 s[6:7], vcc
	v_readlane_b32 s70, v254, 56
	v_readlane_b32 s71, v254, 57
	v_readlane_b32 s38, v254, 58
	v_readlane_b32 s51, v254, 60
	v_readlane_b32 s76, v254, 61
	v_readlane_b32 s83, v254, 62
	s_movk_i32 s59, 0x48
	s_movk_i32 s79, 0x60
	s_movk_i32 s86, 0xff5e
	s_movk_i32 s87, 0xff7d
	v_readlane_b32 s39, v254, 59
	s_cbranch_execz .LBB0_1177
	s_lshl_b32 s9, s68, 11
	s_add_i32 s9, s2, s9
	v_mul_f32_e32 v164, 0x3c800000, v164
	v_lshl_add_u32 v167, v0, 5, s9
	s_waitcnt lgkmcnt(0)
	v_add_f32_e32 v165, v165, v166
	ds_write_b64 v167, v[164:165] offset:512
.LBB0_1177:
	s_or_b64 exec, exec, s[6:7]
	v_mov_b32_e32 v164, v135
	v_mov_b32_e32 v165, v136
	s_waitcnt lgkmcnt(0)
	v_mov_b32_e32 v166, v134
	v_mov_b32_e32 v167, v137
	v_pk_add_f32 v[164:165], v[164:165], v[166:167]
	v_mov_b32_e32 v166, v95
	v_mov_b32_e32 v167, v96
	v_mov_b32_e32 v168, v94
	v_mov_b32_e32 v169, v97
	v_pk_add_f32 v[166:167], v[166:167], v[168:169]
	v_add_f32_e32 v164, v164, v165
	v_pk_add_f32 v[166:167], v[166:167], v[166:167] op_sel:[0,1] op_sel_hi:[1,0]
	v_add_f32_e32 v164, 0, v164
	v_add_f32_e32 v168, v66, v67
	v_add_f32_e32 v170, v68, v69
	v_mov_b32_e32 v165, v42
	v_mov_b32_e32 v167, v43
	v_mov_b32_e32 v169, v44
	v_mov_b32_e32 v171, v45
	v_pk_add_f32 v[164:165], v[164:165], v[166:167]
	v_pk_add_f32 v[166:167], v[168:169], v[170:171]
	s_nop 0
	v_pk_add_f32 v[164:165], v[164:165], v[166:167]
	s_nop 0
	v_add_f32_e32 v164, v164, v165
	v_mov_b32_e32 v165, v164
	s_nop 1
	v_permlane16_swap_b32_e32 v165, v164
	s_waitcnt lgkmcnt(0)
	v_add_f32_e32 v164, v164, v165
	v_mov_b32_e32 v165, v164
	s_nop 1
	v_permlane32_swap_b32_e32 v165, v164
	s_waitcnt lgkmcnt(0)
	v_add_f32_e32 v164, v164, v165
	v_fmamk_f32 v166, v164, 0xbc800000, v137
	v_fmamk_f32 v168, v164, 0xbc800000, v135
	v_fmamk_f32 v165, v164, 0xbc800000, v136
	v_fmamk_f32 v167, v164, 0xbc800000, v134
	v_mul_f32_e32 v168, v168, v168
	v_mul_f32_e32 v166, v166, v166
	v_fmac_f32_e32 v168, v167, v167
	v_fmac_f32_e32 v166, v165, v165
	v_fmamk_f32 v167, v164, 0xbc800000, v97
	v_fmamk_f32 v169, v164, 0xbc800000, v95
	v_add_f32_e32 v165, v168, v166
	v_fmamk_f32 v166, v164, 0xbc800000, v96
	v_fmamk_f32 v168, v164, 0xbc800000, v94
	v_mul_f32_e32 v169, v169, v169
	v_mul_f32_e32 v167, v167, v167
	v_fmac_f32_e32 v169, v168, v168
	v_fmac_f32_e32 v167, v166, v166
	v_add_f32_e32 v166, v169, v167
	v_fmamk_f32 v167, v164, 0xbc800000, v69
	v_fmamk_f32 v169, v164, 0xbc800000, v67
	v_add_f32_e32 v165, v165, v166
	v_fmamk_f32 v166, v164, 0xbc800000, v68
	v_fmamk_f32 v168, v164, 0xbc800000, v66
	v_mul_f32_e32 v169, v169, v169
	v_mul_f32_e32 v167, v167, v167
	v_fmac_f32_e32 v169, v168, v168
	v_fmac_f32_e32 v167, v166, v166
	v_add_f32_e32 v166, v169, v167
	v_fmamk_f32 v167, v164, 0xbc800000, v45
	v_fmamk_f32 v169, v164, 0xbc800000, v43
	v_add_f32_e32 v165, v166, v165
	v_fmamk_f32 v166, v164, 0xbc800000, v44
	v_fmamk_f32 v168, v164, 0xbc800000, v42
	v_mul_f32_e32 v169, v169, v169
	v_mul_f32_e32 v167, v167, v167
	v_fmac_f32_e32 v169, v168, v168
	v_fmac_f32_e32 v167, v166, v166
	v_add_f32_e32 v166, v169, v167
	v_add_f32_e32 v165, v166, v165
	v_mov_b32_e32 v166, v165
	s_nop 1
	v_permlane16_swap_b32_e32 v166, v165
	s_waitcnt lgkmcnt(0)
	v_add_f32_e32 v165, v165, v166
	v_mov_b32_e32 v166, v165
	s_nop 1
	v_permlane32_swap_b32_e32 v166, v165
	s_and_saveexec_b64 s[6:7], vcc
	s_cbranch_execz .LBB0_1179
	s_lshl_b32 s9, s68, 11
	s_add_i32 s9, s2, s9
	v_mul_f32_e32 v164, 0x3c800000, v164
	v_lshl_add_u32 v167, v0, 5, s9
	s_waitcnt lgkmcnt(0)
	v_add_f32_e32 v165, v165, v166
	ds_write_b64 v167, v[164:165] offset:1024
.LBB0_1179:
	s_or_b64 exec, exec, s[6:7]
	v_mov_b32_e32 v164, v119
	v_mov_b32_e32 v165, v120
	s_waitcnt lgkmcnt(0)
	v_mov_b32_e32 v166, v118
	v_mov_b32_e32 v167, v121
	v_pk_add_f32 v[164:165], v[164:165], v[166:167]
	v_mov_b32_e32 v166, v91
	v_mov_b32_e32 v167, v92
	v_mov_b32_e32 v168, v90
	v_mov_b32_e32 v169, v93
	v_pk_add_f32 v[166:167], v[166:167], v[168:169]
	v_add_f32_e32 v164, v164, v165
	v_pk_add_f32 v[166:167], v[166:167], v[166:167] op_sel:[0,1] op_sel_hi:[1,0]
	v_add_f32_e32 v164, 0, v164
	v_add_f32_e32 v168, v58, v59
	v_add_f32_e32 v170, v60, v61
	v_mov_b32_e32 v165, v34
	v_mov_b32_e32 v167, v35
	v_mov_b32_e32 v169, v36
	v_mov_b32_e32 v171, v37
	v_pk_add_f32 v[164:165], v[164:165], v[166:167]
	v_pk_add_f32 v[166:167], v[168:169], v[170:171]
	s_nop 0
	v_pk_add_f32 v[164:165], v[164:165], v[166:167]
	s_nop 0
	v_add_f32_e32 v164, v164, v165
	v_mov_b32_e32 v165, v164
	s_nop 1
	v_permlane16_swap_b32_e32 v165, v164
	s_waitcnt lgkmcnt(0)
	v_add_f32_e32 v164, v164, v165
	v_mov_b32_e32 v165, v164
	s_nop 1
	v_permlane32_swap_b32_e32 v165, v164
	s_waitcnt lgkmcnt(0)
	v_add_f32_e32 v164, v164, v165
	v_fmamk_f32 v166, v164, 0xbc800000, v121
	v_fmamk_f32 v168, v164, 0xbc800000, v119
	v_fmamk_f32 v165, v164, 0xbc800000, v120
	v_fmamk_f32 v167, v164, 0xbc800000, v118
	v_mul_f32_e32 v168, v168, v168
	v_mul_f32_e32 v166, v166, v166
	v_fmac_f32_e32 v168, v167, v167
	v_fmac_f32_e32 v166, v165, v165
	v_fmamk_f32 v167, v164, 0xbc800000, v93
	v_fmamk_f32 v169, v164, 0xbc800000, v91
	v_add_f32_e32 v165, v168, v166
	v_fmamk_f32 v166, v164, 0xbc800000, v92
	v_fmamk_f32 v168, v164, 0xbc800000, v90
	v_mul_f32_e32 v169, v169, v169
	v_mul_f32_e32 v167, v167, v167
	v_fmac_f32_e32 v169, v168, v168
	v_fmac_f32_e32 v167, v166, v166
	v_add_f32_e32 v166, v169, v167
	v_fmamk_f32 v167, v164, 0xbc800000, v61
	v_fmamk_f32 v169, v164, 0xbc800000, v59
	v_add_f32_e32 v165, v165, v166
	v_fmamk_f32 v166, v164, 0xbc800000, v60
	v_fmamk_f32 v168, v164, 0xbc800000, v58
	v_mul_f32_e32 v169, v169, v169
	v_mul_f32_e32 v167, v167, v167
	v_fmac_f32_e32 v169, v168, v168
	v_fmac_f32_e32 v167, v166, v166
	v_add_f32_e32 v166, v169, v167
	v_fmamk_f32 v167, v164, 0xbc800000, v37
	v_fmamk_f32 v169, v164, 0xbc800000, v35
	v_add_f32_e32 v165, v166, v165
	v_fmamk_f32 v166, v164, 0xbc800000, v36
	v_fmamk_f32 v168, v164, 0xbc800000, v34
	v_mul_f32_e32 v169, v169, v169
	v_mul_f32_e32 v167, v167, v167
	v_fmac_f32_e32 v169, v168, v168
	v_fmac_f32_e32 v167, v166, v166
	v_add_f32_e32 v166, v169, v167
	v_add_f32_e32 v165, v166, v165
	v_mov_b32_e32 v166, v165
	s_nop 1
	v_permlane16_swap_b32_e32 v166, v165
	s_waitcnt lgkmcnt(0)
	v_add_f32_e32 v165, v165, v166
	v_mov_b32_e32 v166, v165
	s_nop 1
	v_permlane32_swap_b32_e32 v166, v165
	s_and_saveexec_b64 s[6:7], vcc
	s_cbranch_execz .LBB0_1181
	s_lshl_b32 s9, s68, 11
	s_add_i32 s9, s2, s9
	v_mul_f32_e32 v164, 0x3c800000, v164
	v_lshl_add_u32 v167, v0, 5, s9
	s_waitcnt lgkmcnt(0)
	v_add_f32_e32 v165, v165, v166
	ds_write_b64 v167, v[164:165] offset:1536
.LBB0_1181:
	s_or_b64 exec, exec, s[6:7]
	v_mov_b32_e32 v164, v123
	v_mov_b32_e32 v165, v124
	s_waitcnt lgkmcnt(0)
	v_mov_b32_e32 v166, v122
	v_mov_b32_e32 v167, v125
	v_pk_add_f32 v[164:165], v[164:165], v[166:167]
	v_mov_b32_e32 v166, v87
	v_mov_b32_e32 v167, v88
	v_mov_b32_e32 v168, v86
	v_mov_b32_e32 v169, v89
	v_pk_add_f32 v[166:167], v[166:167], v[168:169]
	v_add_f32_e32 v164, v164, v165
	v_pk_add_f32 v[166:167], v[166:167], v[166:167] op_sel:[0,1] op_sel_hi:[1,0]
	v_add_f32_e32 v164, 0, v164
	v_add_f32_e32 v168, v54, v55
	v_add_f32_e32 v170, v56, v57
	v_mov_b32_e32 v165, v30
	v_mov_b32_e32 v167, v31
	v_mov_b32_e32 v169, v32
	v_mov_b32_e32 v171, v33
	v_pk_add_f32 v[164:165], v[164:165], v[166:167]
	v_pk_add_f32 v[166:167], v[168:169], v[170:171]
	s_nop 0
	v_pk_add_f32 v[164:165], v[164:165], v[166:167]
	s_nop 0
	v_add_f32_e32 v164, v164, v165
	v_mov_b32_e32 v165, v164
	s_nop 1
	v_permlane16_swap_b32_e32 v165, v164
	s_waitcnt lgkmcnt(0)
	v_add_f32_e32 v164, v164, v165
	v_mov_b32_e32 v165, v164
	s_nop 1
	v_permlane32_swap_b32_e32 v165, v164
	s_waitcnt lgkmcnt(0)
	v_add_f32_e32 v164, v164, v165
	v_fmamk_f32 v166, v164, 0xbc800000, v125
	v_fmamk_f32 v168, v164, 0xbc800000, v123
	v_fmamk_f32 v165, v164, 0xbc800000, v124
	v_fmamk_f32 v167, v164, 0xbc800000, v122
	v_mul_f32_e32 v168, v168, v168
	v_mul_f32_e32 v166, v166, v166
	v_fmac_f32_e32 v168, v167, v167
	v_fmac_f32_e32 v166, v165, v165
	v_fmamk_f32 v167, v164, 0xbc800000, v89
	v_fmamk_f32 v169, v164, 0xbc800000, v87
	v_add_f32_e32 v165, v168, v166
	v_fmamk_f32 v166, v164, 0xbc800000, v88
	v_fmamk_f32 v168, v164, 0xbc800000, v86
	v_mul_f32_e32 v169, v169, v169
	v_mul_f32_e32 v167, v167, v167
	v_fmac_f32_e32 v169, v168, v168
	v_fmac_f32_e32 v167, v166, v166
	v_add_f32_e32 v166, v169, v167
	v_fmamk_f32 v167, v164, 0xbc800000, v57
	v_fmamk_f32 v169, v164, 0xbc800000, v55
	v_add_f32_e32 v165, v165, v166
	v_fmamk_f32 v166, v164, 0xbc800000, v56
	v_fmamk_f32 v168, v164, 0xbc800000, v54
	v_mul_f32_e32 v169, v169, v169
	v_mul_f32_e32 v167, v167, v167
	v_fmac_f32_e32 v169, v168, v168
	v_fmac_f32_e32 v167, v166, v166
	v_add_f32_e32 v166, v169, v167
	v_fmamk_f32 v167, v164, 0xbc800000, v33
	v_fmamk_f32 v169, v164, 0xbc800000, v31
	v_add_f32_e32 v165, v166, v165
	v_fmamk_f32 v166, v164, 0xbc800000, v32
	v_fmamk_f32 v168, v164, 0xbc800000, v30
	v_mul_f32_e32 v169, v169, v169
	v_mul_f32_e32 v167, v167, v167
	v_fmac_f32_e32 v169, v168, v168
	v_fmac_f32_e32 v167, v166, v166
	v_add_f32_e32 v166, v169, v167
	v_add_f32_e32 v165, v166, v165
	v_mov_b32_e32 v166, v165
	s_nop 1
	v_permlane16_swap_b32_e32 v166, v165
	s_waitcnt lgkmcnt(0)
	v_add_f32_e32 v165, v165, v166
	v_mov_b32_e32 v166, v165
	s_nop 1
	v_permlane32_swap_b32_e32 v166, v165
	s_and_saveexec_b64 s[6:7], vcc
	s_cbranch_execz .LBB0_1183
	s_lshl_b32 s9, s68, 11
	s_add_i32 s9, s2, s9
	v_mul_f32_e32 v164, 0x3c800000, v164
	v_lshl_add_u32 v167, v0, 5, s9
	s_waitcnt lgkmcnt(0)
	v_add_f32_e32 v165, v165, v166
	ds_write_b64 v167, v[164:165] offset:4096
.LBB0_1183:
	s_or_b64 exec, exec, s[6:7]
	v_mov_b32_e32 v164, v115
	v_mov_b32_e32 v165, v116
	s_waitcnt lgkmcnt(0)
	v_mov_b32_e32 v166, v114
	v_mov_b32_e32 v167, v117
	v_pk_add_f32 v[164:165], v[164:165], v[166:167]
	v_mov_b32_e32 v166, v83
	v_mov_b32_e32 v167, v84
	v_mov_b32_e32 v168, v82
	v_mov_b32_e32 v169, v85
	v_pk_add_f32 v[166:167], v[166:167], v[168:169]
	v_add_f32_e32 v164, v164, v165
	v_pk_add_f32 v[166:167], v[166:167], v[166:167] op_sel:[0,1] op_sel_hi:[1,0]
	v_add_f32_e32 v164, 0, v164
	v_add_f32_e32 v168, v50, v51
	v_add_f32_e32 v170, v52, v53
	v_mov_b32_e32 v165, v26
	v_mov_b32_e32 v167, v27
	v_mov_b32_e32 v169, v28
	v_mov_b32_e32 v171, v29
	v_pk_add_f32 v[164:165], v[164:165], v[166:167]
	v_pk_add_f32 v[166:167], v[168:169], v[170:171]
	s_nop 0
	v_pk_add_f32 v[164:165], v[164:165], v[166:167]
	s_nop 0
	v_add_f32_e32 v164, v164, v165
	v_mov_b32_e32 v165, v164
	s_nop 1
	v_permlane16_swap_b32_e32 v165, v164
	s_waitcnt lgkmcnt(0)
	v_add_f32_e32 v164, v164, v165
	v_mov_b32_e32 v165, v164
	s_nop 1
	v_permlane32_swap_b32_e32 v165, v164
	s_waitcnt lgkmcnt(0)
	v_add_f32_e32 v164, v164, v165
	v_fmamk_f32 v166, v164, 0xbc800000, v117
	v_fmamk_f32 v168, v164, 0xbc800000, v115
	v_fmamk_f32 v165, v164, 0xbc800000, v116
	v_fmamk_f32 v167, v164, 0xbc800000, v114
	v_mul_f32_e32 v168, v168, v168
	v_mul_f32_e32 v166, v166, v166
	v_fmac_f32_e32 v168, v167, v167
	v_fmac_f32_e32 v166, v165, v165
	v_fmamk_f32 v167, v164, 0xbc800000, v85
	v_fmamk_f32 v169, v164, 0xbc800000, v83
	v_add_f32_e32 v165, v168, v166
	v_fmamk_f32 v166, v164, 0xbc800000, v84
	v_fmamk_f32 v168, v164, 0xbc800000, v82
	v_mul_f32_e32 v169, v169, v169
	v_mul_f32_e32 v167, v167, v167
	v_fmac_f32_e32 v169, v168, v168
	v_fmac_f32_e32 v167, v166, v166
	v_add_f32_e32 v166, v169, v167
	v_fmamk_f32 v167, v164, 0xbc800000, v53
	v_fmamk_f32 v169, v164, 0xbc800000, v51
	v_add_f32_e32 v165, v165, v166
	v_fmamk_f32 v166, v164, 0xbc800000, v52
	v_fmamk_f32 v168, v164, 0xbc800000, v50
	v_mul_f32_e32 v169, v169, v169
	v_mul_f32_e32 v167, v167, v167
	v_fmac_f32_e32 v169, v168, v168
	v_fmac_f32_e32 v167, v166, v166
	v_add_f32_e32 v166, v169, v167
	v_fmamk_f32 v167, v164, 0xbc800000, v29
	v_fmamk_f32 v169, v164, 0xbc800000, v27
	v_add_f32_e32 v165, v166, v165
	v_fmamk_f32 v166, v164, 0xbc800000, v28
	v_fmamk_f32 v168, v164, 0xbc800000, v26
	v_mul_f32_e32 v169, v169, v169
	v_mul_f32_e32 v167, v167, v167
	v_fmac_f32_e32 v169, v168, v168
	v_fmac_f32_e32 v167, v166, v166
	v_add_f32_e32 v166, v169, v167
	v_add_f32_e32 v165, v166, v165
	v_mov_b32_e32 v166, v165
	s_nop 1
	v_permlane16_swap_b32_e32 v166, v165
	s_waitcnt lgkmcnt(0)
	v_add_f32_e32 v165, v165, v166
	v_mov_b32_e32 v166, v165
	s_nop 1
	v_permlane32_swap_b32_e32 v166, v165
	s_and_saveexec_b64 s[6:7], vcc
	s_cbranch_execz .LBB0_1185
	s_lshl_b32 s9, s68, 11
	s_add_i32 s9, s2, s9
	v_mul_f32_e32 v164, 0x3c800000, v164
	v_lshl_add_u32 v167, v0, 5, s9
	s_waitcnt lgkmcnt(0)
	v_add_f32_e32 v165, v165, v166
	ds_write_b64 v167, v[164:165] offset:4608
.LBB0_1185:
	s_or_b64 exec, exec, s[6:7]
	v_mov_b32_e32 v164, v111
	v_mov_b32_e32 v165, v112
	s_waitcnt lgkmcnt(0)
	v_mov_b32_e32 v166, v110
	v_mov_b32_e32 v167, v113
	v_pk_add_f32 v[164:165], v[164:165], v[166:167]
	v_mov_b32_e32 v166, v79
	v_mov_b32_e32 v167, v80
	v_mov_b32_e32 v168, v78
	v_mov_b32_e32 v169, v81
	v_pk_add_f32 v[166:167], v[166:167], v[168:169]
	v_add_f32_e32 v164, v164, v165
	v_pk_add_f32 v[166:167], v[166:167], v[166:167] op_sel:[0,1] op_sel_hi:[1,0]
	v_add_f32_e32 v164, 0, v164
	v_add_f32_e32 v168, v46, v47
	v_add_f32_e32 v170, v48, v49
	v_mov_b32_e32 v165, v6
	v_mov_b32_e32 v167, v7
	v_mov_b32_e32 v169, v8
	v_mov_b32_e32 v171, v9
	v_pk_add_f32 v[164:165], v[164:165], v[166:167]
	v_pk_add_f32 v[166:167], v[168:169], v[170:171]
	s_nop 0
	v_pk_add_f32 v[164:165], v[164:165], v[166:167]
	s_nop 0
	v_add_f32_e32 v164, v164, v165
	v_mov_b32_e32 v165, v164
	s_nop 1
	v_permlane16_swap_b32_e32 v165, v164
	s_waitcnt lgkmcnt(0)
	v_add_f32_e32 v164, v164, v165
	v_mov_b32_e32 v165, v164
	s_nop 1
	v_permlane32_swap_b32_e32 v165, v164
	s_waitcnt lgkmcnt(0)
	v_add_f32_e32 v164, v164, v165
	v_fmamk_f32 v166, v164, 0xbc800000, v113
	v_fmamk_f32 v168, v164, 0xbc800000, v111
	v_fmamk_f32 v165, v164, 0xbc800000, v112
	v_fmamk_f32 v167, v164, 0xbc800000, v110
	v_mul_f32_e32 v168, v168, v168
	v_mul_f32_e32 v166, v166, v166
	v_fmac_f32_e32 v168, v167, v167
	v_fmac_f32_e32 v166, v165, v165
	v_fmamk_f32 v167, v164, 0xbc800000, v81
	v_fmamk_f32 v169, v164, 0xbc800000, v79
	v_add_f32_e32 v165, v168, v166
	v_fmamk_f32 v166, v164, 0xbc800000, v80
	v_fmamk_f32 v168, v164, 0xbc800000, v78
	v_mul_f32_e32 v169, v169, v169
	v_mul_f32_e32 v167, v167, v167
	v_fmac_f32_e32 v169, v168, v168
	v_fmac_f32_e32 v167, v166, v166
	v_add_f32_e32 v166, v169, v167
	v_fmamk_f32 v167, v164, 0xbc800000, v49
	v_fmamk_f32 v169, v164, 0xbc800000, v47
	v_add_f32_e32 v165, v165, v166
	v_fmamk_f32 v166, v164, 0xbc800000, v48
	v_fmamk_f32 v168, v164, 0xbc800000, v46
	v_mul_f32_e32 v169, v169, v169
	v_mul_f32_e32 v167, v167, v167
	v_fmac_f32_e32 v169, v168, v168
	v_fmac_f32_e32 v167, v166, v166
	v_add_f32_e32 v166, v169, v167
	v_fmamk_f32 v167, v164, 0xbc800000, v9
	v_fmamk_f32 v169, v164, 0xbc800000, v7
	v_add_f32_e32 v165, v166, v165
	v_fmamk_f32 v166, v164, 0xbc800000, v8
	v_fmamk_f32 v168, v164, 0xbc800000, v6
	v_mul_f32_e32 v169, v169, v169
	v_mul_f32_e32 v167, v167, v167
	v_fmac_f32_e32 v169, v168, v168
	v_fmac_f32_e32 v167, v166, v166
	v_add_f32_e32 v166, v169, v167
	v_add_f32_e32 v165, v166, v165
	v_mov_b32_e32 v166, v165
	s_nop 1
	v_permlane16_swap_b32_e32 v166, v165
	s_waitcnt lgkmcnt(0)
	v_add_f32_e32 v165, v165, v166
	v_mov_b32_e32 v166, v165
	s_nop 1
	v_permlane32_swap_b32_e32 v166, v165
	s_and_saveexec_b64 s[6:7], vcc
	s_cbranch_execz .LBB0_1187
	s_lshl_b32 s9, s68, 11
	s_add_i32 s9, s2, s9
	v_mul_f32_e32 v164, 0x3c800000, v164
	v_lshl_add_u32 v167, v0, 5, s9
	s_waitcnt lgkmcnt(0)
	v_add_f32_e32 v165, v165, v166
	ds_write_b64 v167, v[164:165] offset:5120
.LBB0_1187:
	s_or_b64 exec, exec, s[6:7]
	v_mov_b32_e32 v164, v107
	v_mov_b32_e32 v165, v108
	s_waitcnt lgkmcnt(0)
	v_mov_b32_e32 v166, v106
	v_mov_b32_e32 v167, v109
	v_pk_add_f32 v[164:165], v[164:165], v[166:167]
	v_mov_b32_e32 v166, v75
	v_mov_b32_e32 v167, v76
	v_mov_b32_e32 v168, v74
	v_mov_b32_e32 v169, v77
	v_pk_add_f32 v[166:167], v[166:167], v[168:169]
	v_add_f32_e32 v164, v164, v165
	v_pk_add_f32 v[166:167], v[166:167], v[166:167] op_sel:[0,1] op_sel_hi:[1,0]
	v_add_f32_e32 v164, 0, v164
	v_add_f32_e32 v168, v38, v39
	v_add_f32_e32 v170, v40, v41
	v_mov_b32_e32 v165, v2
	v_mov_b32_e32 v167, v3
	v_mov_b32_e32 v169, v4
	v_mov_b32_e32 v171, v5
	v_pk_add_f32 v[164:165], v[164:165], v[166:167]
	v_pk_add_f32 v[166:167], v[168:169], v[170:171]
	s_nop 0
	v_pk_add_f32 v[164:165], v[164:165], v[166:167]
	s_nop 0
	v_add_f32_e32 v164, v164, v165
	v_mov_b32_e32 v165, v164
	s_nop 1
	v_permlane16_swap_b32_e32 v165, v164
	s_waitcnt lgkmcnt(0)
	v_add_f32_e32 v164, v164, v165
	v_mov_b32_e32 v165, v164
	s_nop 1
	v_permlane32_swap_b32_e32 v165, v164
	s_waitcnt lgkmcnt(0)
	v_add_f32_e32 v164, v164, v165
	v_fmamk_f32 v166, v164, 0xbc800000, v109
	v_fmamk_f32 v168, v164, 0xbc800000, v107
	v_fmamk_f32 v165, v164, 0xbc800000, v108
	v_fmamk_f32 v167, v164, 0xbc800000, v106
	v_mul_f32_e32 v168, v168, v168
	v_mul_f32_e32 v166, v166, v166
	v_fmac_f32_e32 v168, v167, v167
	v_fmac_f32_e32 v166, v165, v165
	v_fmamk_f32 v167, v164, 0xbc800000, v77
	v_fmamk_f32 v169, v164, 0xbc800000, v75
	v_add_f32_e32 v165, v168, v166
	v_fmamk_f32 v166, v164, 0xbc800000, v76
	v_fmamk_f32 v168, v164, 0xbc800000, v74
	v_mul_f32_e32 v169, v169, v169
	v_mul_f32_e32 v167, v167, v167
	v_fmac_f32_e32 v169, v168, v168
	v_fmac_f32_e32 v167, v166, v166
	v_add_f32_e32 v166, v169, v167
	v_fmamk_f32 v167, v164, 0xbc800000, v41
	v_fmamk_f32 v169, v164, 0xbc800000, v39
	v_add_f32_e32 v165, v165, v166
	v_fmamk_f32 v166, v164, 0xbc800000, v40
	v_fmamk_f32 v168, v164, 0xbc800000, v38
	v_mul_f32_e32 v169, v169, v169
	v_mul_f32_e32 v167, v167, v167
	v_fmac_f32_e32 v169, v168, v168
	v_fmac_f32_e32 v167, v166, v166
	v_add_f32_e32 v166, v169, v167
	v_fmamk_f32 v167, v164, 0xbc800000, v5
	v_fmamk_f32 v169, v164, 0xbc800000, v3
	v_add_f32_e32 v165, v166, v165
	v_fmamk_f32 v166, v164, 0xbc800000, v4
	v_fmamk_f32 v168, v164, 0xbc800000, v2
	v_mul_f32_e32 v169, v169, v169
	v_mul_f32_e32 v167, v167, v167
	v_fmac_f32_e32 v169, v168, v168
	v_fmac_f32_e32 v167, v166, v166
	v_add_f32_e32 v166, v169, v167
	v_add_f32_e32 v165, v166, v165
	v_mov_b32_e32 v162, v165
	s_nop 1
	v_permlane16_swap_b32_e32 v162, v165
	s_waitcnt lgkmcnt(0)
	v_add_f32_e32 v162, v165, v162
	v_mov_b32_e32 v163, v162
	s_nop 1
	v_permlane32_swap_b32_e32 v163, v162
	s_and_saveexec_b64 s[6:7], vcc
	s_cbranch_execz .LBB0_1189
	s_lshl_b32 s9, s68, 11
	s_add_i32 s2, s2, s9
	v_mul_f32_e32 v164, 0x3c800000, v164
	v_lshl_add_u32 v166, v0, 5, s2
	s_waitcnt lgkmcnt(0)
	v_add_f32_e32 v165, v162, v163
	ds_write_b64 v166, v[164:165] offset:5632
